# split retention (2 workgroups per head) + 2 producers per head on 128 workgroups + 8 producer waves + sync only on publish rounds + wide producer stores
# speedup vs baseline: 1.0009x; 1.0009x over previous
; DEVINL void phase_mixers(const Ctx& c, int layer, unsigned char* lds) {
;     ...
;     if (bx < 64) { rwkv_scan(c, layer, bx >> 3, bx & 7, cnts + bx * 3, bx < 32 ? 3 : 2, (float*)lds); return; }
;     if (bx < 96) ret_block(c, (bx - 64) >> 2, (bx - 64) & 3, lds);
;     else {
;         if (bx < 256) {
;             const int idx = bx - 96;
;             int head, pj, nP;
;             if (idx < 96) { head = idx / 3; pj = idx - head * 3; nP = 3; } else { const int j = idx - 96; head = 32 + (j >> 1); pj = j & 1; nP = 2; }
;             rw_project_head(c, layer, head >> 3, head & 7, pj, nP, cnts + head * 3 + pj, lds);
.LBB0_93:
	s_and_b64 vcc, exec, s[0:1]
	s_cbranch_vccz .LBB0_352
	v_readlane_b32 s0, v247, 0
	s_mov_b32 s95, s0
	s_cmp_gt_i32 s95, 63
	s_mov_b64 s[0:1], -1
	s_cbranch_scc0 .LBB0_293
	v_readlane_b32 s26, v247, 7
	s_cmpk_gt_u32 s95, 0x7f
	v_readlane_b32 s27, v247, 8
	s_mov_b64 s[68:69], 0x10280
	s_mov_b64 s[70:71], 0x10300
	s_cbranch_scc0 .LBB0_266
	s_cmpk_gt_u32 s95, 0xff
	s_cbranch_scc1 .LBB0_240
	s_cmpk_gt_u32 s95, 0x7f
	s_cbranch_scc0 .LBB0_99
	s_add_i32 s0, s95, 0xffffff80
	s_lshr_b32 s0, s0, 1
	s_add_i32 s29, s0, 0
	s_and_b32 s28, s95, 1
	s_mov_b64 s[0:1], 0

;     DEVINL bf16_t* Z() const { return (bf16_t*)(ws + OFF_Z); }
;     DEVINL bf16_t* RW() const { return (bf16_t*)(ws + OFF_RW); }
; #define TID (opq_v((int)threadIdx.x))
; DEVINL void rw_project_head(const Ctx& c, int layer, int b, int hd, int pj, int nP, unsigned* cnt, unsigned char* lds) {
;     const int tid = TID, lane = tid & 63, w = tid >> 6, cl = lane & 15, kg = lane >> 4;
;     bf16_t* BW = (bf16_t*)lds;
;     bf16_t* ACT = (bf16_t*)(lds + RP_BW_BYTES + (w < RP_NW ? w : 0) * RP_WAVE_BYTES);
;     bf16_t* RKV = ACT + 16 * RP_KP;
;     const float* mu = c.in[I_MU] + layer * 1792;
;     __syncthreads();
;     {
;         const float* w2 = c.in[I_W2] + (size_t)layer * 64 * 512 + hd * 64;
;         const float* a2 = c.in[I_A2] + (size_t)layer * 64 * 512 + hd * 64;
;         const float* g2 = c.in[I_G2] + (size_t)layer * 128 * 512 + hd * 64;
;         const float* v2 = c.in[I_V2] + (size_t)(layer > 0 ? layer - 1 : 0) * 32 * 512 + hd * 64;
;         for (int e = tid; e < 64 * 288; e += NTHR) {
;             const int k = e >> 6, col = e & 63;
;             float v;
;             if (k < 64) v = w2[(size_t)k * 512 + col];
;             else if (k < 128) v = a2[(size_t)(k - 64) * 512 + col];
;             else if (k < 256) v = g2[(size_t)(k - 128) * 512 + col];
;             else v = layer > 0 ? v2[(size_t)(k - 256) * 512 + col] : 0.f;
;             BW[col * RP_KP + k] = f2bf(v);
;         }
;     }
;     float w0c[4], a0c[4], kkc[4], kac[4], v0c[4];
; #pragma unroll
;     for (int nt = 0; nt < 4; ++nt) {
;         const int col = layer * 512 + hd * 64 + nt * 16 + cl;
;         w0c[nt] = c.in[I_W0][col]; a0c[nt] = c.in[I_A0][col]; kkc[nt] = c.in[I_KKW][col]; kac[nt] = c.in[I_KAW][col];
;         v0c[nt] = layer > 0 ? c.in[I_V0][(layer - 1) * 512 + hd * 64 + nt * 16 + cl] : 0.f;
;     }
;     bf16_t* R = c.RW(); bf16_t* LD = c.RW() + (size_t)T * 512; bf16_t* KP = c.RW() + (size_t)2 * T * 512; bf16_t* VP = c.RW() + (size_t)3 * T * 512;
;     bf16_t* KK = c.RW() + (size_t)4 * T * 512; bf16_t* BB = c.RW() + (size_t)5 * T * 512; bf16_t* GG = c.RW() + (size_t)6 * T * 512;
;     const bf16_t* Zb = c.Z();
;     int round = 0;
;     for (int q0 = 0; nP * q0 + pj < RP_NG; q0 += RP_NW, ++round) {
;         const int g = nP * (q0 + w) + pj;
;         const bool act = (w < RP_NW) && (g < RP_NG);
;         const int t0 = b * L + g * 16;
.LBB0_139:
	s_mul_i32 s66, s29, 3
	s_lshr_b32 s18, s29, 3
	s_lshl_b64 s[0:1], s[66:67], 2
	v_readlane_b32 s4, v247, 28
	s_add_u32 s4, s4, s0
	v_readlane_b32 s0, v247, 29
	s_addc_u32 s5, s0, s1
	s_ashr_i32 s29, s28, 31
	s_lshl_b64 s[0:1], s[28:29], 2
	s_add_u32 s8, s4, s0
	v_ashrrev_i32_e32 v6, 6, v15
	s_movk_i32 s0, 0x3d00
	s_addc_u32 s9, s5, s1
	v_mul_lo_u32 v0, v6, s0
	v_readlane_b32 s0, v245, 32
	v_readlane_b32 s1, v245, 33
	s_mov_b32 s12, s0
	s_mulk_i32 s0, 0x700
	s_ashr_i32 s1, s0, 31
	v_readlane_b32 s68, v246, 43
	s_lshl_b64 s[0:1], s[0:1], 2
	v_readlane_b32 s76, v246, 51
	v_cmp_gt_i32_e64 s[6:7], 8, v6
	v_readlane_b32 s77, v246, 52
	s_add_u32 s0, s76, s0
	v_and_b32_e32 v2, 31, v15
	v_cndmask_b32_e64 v0, 0, v0, s[6:7]
	s_addc_u32 s1, s77, s1
	v_lshlrev_b32_e32 v64, 5, v2
	v_add_u32_e32 v7, 0, v0
	v_lshl_add_u64 v[0:1], s[0:1], 0, v[64:65]
	s_mov_b64 s[4:5], 0x1800
	s_sub_i32 s17, 0x88, s28
	v_lshlrev_b32_e32 v78, 3, v2
	v_lshl_add_u64 v[80:81], v[0:1], 0, s[4:5]
	v_cmp_gt_u32_e32 vcc, 8, v2
	v_and_b32_e32 v0, 24, v15
	v_lshl_add_u32 v1, v2, 4, v7
	v_lshlrev_b32_e32 v2, 3, v15
	s_lshl_b32 s10, s31, 2
	v_cmp_eq_u32_e64 s[4:5], 8, v0
	v_lshrrev_b32_e32 v9, 2, v14
	v_and_b32_e32 v0, 24, v2
	v_and_b32_e32 v11, 56, v2
	s_add_u32 s0, s0, s10
	v_mul_u32_u24_e32 v3, 0x250, v9
	v_lshlrev_b32_e32 v4, 1, v0
	v_or_b32_e32 v2, s31, v11
	s_addc_u32 s1, s1, 0
	v_lshlrev_b32_e32 v64, 2, v11
	v_add3_u32 v176, v7, v3, v4
	v_or_b32_e32 v12, 0x800, v2
	v_lshl_add_u64 v[2:3], s[0:1], 0, v[64:65]
	s_movk_i32 s0, 0x250
	v_mad_u32_u24 v177, v10, s0, v7
	s_movk_i32 s0, 0xfdb2
	v_mad_i32_i24 v17, v10, s0, v177
	v_readlane_b32 s0, v247, 1
	v_readlane_b32 s1, v247, 2
	s_mov_b32 s1, 0xaaaaaab
	s_movk_i32 s13, 0xffe8
	v_mul_hi_u32 v18, v14, s1
	v_lshrrev_b32_e32 v4, 2, v15
	v_mad_i32_i24 v19, v18, s13, v14
	v_and_b32_e32 v178, 48, v15
	v_and_b32_e32 v15, 12, v4
	v_lshlrev_b32_e32 v4, 6, v19
	v_and_b32_e32 v4, 0xfffffe00, v4
	v_add_u32_e32 v4, v4, v12
	v_ashrrev_i32_e32 v5, 31, v4
	v_lshl_add_u64 v[88:89], v[4:5], 1, s[26:27]
	v_or_b32_e32 v4, 64, v14
	v_mul_hi_u32 v20, v4, s1
	v_mad_i32_i24 v21, v20, s13, v4
	v_lshlrev_b32_e32 v4, 6, v21
	v_and_b32_e32 v4, 0xfffffe00, v4
	v_add_u32_e32 v4, v4, v12
	v_ashrrev_i32_e32 v5, 31, v4
	v_lshl_add_u64 v[90:91], v[4:5], 1, s[26:27]
	v_or_b32_e32 v4, 0x80, v14
	v_mul_hi_u32 v22, v4, s1
	v_mad_i32_i24 v23, v22, s13, v4
	v_lshlrev_b32_e32 v4, 6, v23
	v_and_b32_e32 v4, 0xfffffe00, v4
	v_add_u32_e32 v4, v4, v12
	v_ashrrev_i32_e32 v5, 31, v4
	v_lshl_add_u64 v[92:93], v[4:5], 1, s[26:27]
	v_or_b32_e32 v4, 0xc0, v14
	v_mul_hi_u32 v24, v4, s1
	v_mad_i32_i24 v25, v24, s13, v4
	v_lshlrev_b32_e32 v4, 6, v25
	v_and_b32_e32 v4, 0xfffffe00, v4
	v_add_u32_e32 v4, v4, v12
	v_ashrrev_i32_e32 v5, 31, v4
	v_lshl_add_u64 v[94:95], v[4:5], 1, s[26:27]
	v_or_b32_e32 v4, 0x100, v14
	v_mul_hi_u32 v26, v4, s1
	v_mad_i32_i24 v27, v26, s13, v4
	v_lshlrev_b32_e32 v4, 6, v27
	v_and_b32_e32 v4, 0xfffffe00, v4
	v_add_u32_e32 v4, v4, v12
	v_ashrrev_i32_e32 v5, 31, v4
	v_lshl_add_u64 v[96:97], v[4:5], 1, s[26:27]
	v_or_b32_e32 v4, 0x140, v14
	v_lshrrev_b32_e32 v8, 5, v14
	v_mul_hi_u32 v14, v4, s1
	v_mad_i32_i24 v28, v14, s13, v4
	v_lshlrev_b32_e32 v4, 6, v28
	v_and_b32_e32 v4, 0xfffffe00, v4
	v_add_u32_e32 v4, v4, v12
	v_ashrrev_i32_e32 v5, 31, v4
	v_ashrrev_i32_e32 v12, 3, v19
	v_lshl_add_u64 v[98:99], v[4:5], 1, s[26:27]
	v_lshlrev_b32_e32 v4, 9, v12
	v_ashrrev_i32_e32 v5, 31, v4
	s_movk_i32 s1, 0x180
	v_lshl_add_u64 v[100:101], v[4:5], 2, v[2:3]
	v_mad_u32_u24 v4, v18, s1, v7
	v_lshlrev_b32_e32 v5, 7, v12
	v_lshlrev_b32_e32 v11, 1, v11
	v_ashrrev_i32_e32 v12, 3, v21
	v_add3_u32 v179, v4, v5, v11
	v_lshlrev_b32_e32 v4, 9, v12
	v_ashrrev_i32_e32 v5, 31, v4
	v_lshl_add_u64 v[102:103], v[4:5], 2, v[2:3]
	v_mad_u32_u24 v4, v20, s1, v7
	v_lshlrev_b32_e32 v5, 7, v12
	v_ashrrev_i32_e32 v12, 3, v23
	v_add3_u32 v180, v4, v5, v11
	v_lshlrev_b32_e32 v4, 9, v12
	v_ashrrev_i32_e32 v5, 31, v4
	v_lshl_add_u64 v[104:105], v[4:5], 2, v[2:3]
	v_mad_u32_u24 v4, v22, s1, v7
	v_lshlrev_b32_e32 v5, 7, v12
	v_ashrrev_i32_e32 v12, 3, v25
	v_add3_u32 v181, v4, v5, v11
	v_lshlrev_b32_e32 v4, 9, v12
	v_ashrrev_i32_e32 v5, 31, v4
	v_lshl_add_u64 v[106:107], v[4:5], 2, v[2:3]
	v_mad_u32_u24 v4, v24, s1, v7
	v_lshlrev_b32_e32 v5, 7, v12
	v_ashrrev_i32_e32 v12, 3, v27
	v_add3_u32 v182, v4, v5, v11
	v_lshlrev_b32_e32 v4, 9, v12
	v_ashrrev_i32_e32 v5, 31, v4
	v_lshl_add_u64 v[108:109], v[4:5], 2, v[2:3]
	v_mad_u32_u24 v4, v26, s1, v7
	v_lshlrev_b32_e32 v5, 7, v12
	v_ashrrev_i32_e32 v12, 3, v28
	v_add3_u32 v183, v4, v5, v11
	v_lshlrev_b32_e32 v4, 9, v12
	v_ashrrev_i32_e32 v5, 31, v4
	s_add_i32 s0, s0, 6
	v_lshl_add_u64 v[110:111], v[4:5], 2, v[2:3]
	v_mad_u32_u24 v2, v14, s1, v7
	v_lshlrev_b32_e32 v3, 7, v12
	s_cmp_gt_u32 s0, 14
	v_add3_u32 v184, v2, v3, v11
	v_mul_lo_u32 v3, s30, v6
	v_readlane_b32 s69, v246, 44
	v_readlane_b32 s70, v246, 45
	v_readlane_b32 s71, v246, 46
	v_readlane_b32 s74, v246, 49
	v_readlane_b32 s75, v246, 50
	v_readlane_b32 s78, v246, 53
	v_readlane_b32 s79, v246, 54
	v_readlane_b32 s80, v246, 55
	v_readlane_b32 s81, v246, 56
	v_readlane_b32 s82, v246, 57
	v_readlane_b32 s83, v246, 58
	s_mulk_i32 s18, 0x880
	v_cndmask_b32_e64 v82, 0, 1.0, vcc
	v_cndmask_b32_e64 v84, 1.0, -2.0, vcc
	v_mul_u32_u24_e32 v13, 0x250, v10
	v_add_u32_e32 v16, 0, v178
	v_or_b32_e32 v86, s31, v10
	s_cselect_b64 s[10:11], -1, 0
	s_lshl_b32 s0, s12, 4
	v_mul_u32_u24_e32 v10, 0x250, v8
	v_mul_u32_u24_e32 v2, 0x180, v15
	v_add_u32_e32 v185, s28, v3
	s_mov_b32 s16, 0
	v_cndmask_b32_e32 v175, v163, v164, vcc
	v_or_b32_e32 v112, 16, v86
	v_or_b32_e32 v114, 32, v86
	v_or_b32_e32 v116, 48, v86
	v_mov_b32_e32 v83, v82
	v_mov_b32_e32 v85, v84
	s_or_b32 s19, s0, 1
	s_mul_i32 s20, s30, 8
	v_lshlrev_b32_e32 v186, 4, v185
	v_or_b32_e32 v187, s18, v14
	s_mul_i32 s21, s30, 0x80
	v_or_b32_e32 v188, s18, v26
	v_or_b32_e32 v189, s18, v24
	v_or_b32_e32 v190, s18, v22
	v_or_b32_e32 v191, s18, v20
	v_or_b32_e32 v192, s18, v18
	v_or_b32_e32 v193, s18, v9
	v_or_b32_e32 v194, s18, v8
	v_or_b32_e32 v195, s18, v15
	v_add_u32_e32 v196, v1, v10
	v_lshlrev_b32_e32 v118, 1, v0
	v_add_u32_e32 v197, v16, v13
	v_add_u32_e32 v198, v17, v2
	s_mov_b64 s[74:75], 0x10000
	s_mov_b64 s[76:77], 0x10080
	s_mov_b64 s[78:79], 0x10100
	s_mov_b64 s[80:81], 0x10180
	s_mov_b64 s[82:83], 0x10200
	s_mov_b64 s[68:69], 0x10280
	s_mov_b64 s[70:71], 0x10300
	v_readlane_b32 s72, v246, 47
	v_readlane_b32 s73, v246, 48
	s_waitcnt lgkmcnt(0)
	s_barrier
	s_branch .LBB0_141

; DEVINL void rw_project_head(const Ctx& c, int layer, int b, int hd, int pj, int nP, unsigned* cnt, unsigned char* lds) {
;     ...
;         asm volatile("s_waitcnt vmcnt(0)" ::: "memory");
;         __syncthreads();
;         if (threadIdx.x == 0) {
;             __builtin_amdgcn_fence(__ATOMIC_RELEASE, "agent");
;             __hip_atomic_store(cnt, (unsigned)(layer * 16 + round + 1), __ATOMIC_RELAXED, __HIP_MEMORY_SCOPE_AGENT);
;         }
.LBB0_237:
	s_or_b64 exec, exec, s[12:13]
	s_mov_b64 s[0:1], exec
	s_add_i32 s12, s16, s20
	s_cmp_lt_u32 s12, s17
	s_cbranch_scc0 .Lpub_sync
	s_sub_i32 s13, s19, 1
	s_and_b32 s13, s13, 15
	s_movk_i32 s12, 0x88
	s_movk_i32 s14, 0x88
	s_cmp_eq_u32 s30, 3
	s_cselect_b32 s12, s14, s12
	s_bitcmp1_b32 s12, s13
	s_cbranch_scc0 .LBB0_140
.Lpub_sync:
	s_waitcnt vmcnt(0)
	s_barrier
	v_cmp_eq_u32_e32 vcc, 0x1c0, v160
	s_nop 0
	s_and_b64 s[12:13], s[0:1], vcc
	s_mov_b64 exec, s[12:13]
	s_cbranch_execz .LBB0_140
	v_mov_b32_e32 v0, s19
	buffer_wbl2 sc1
	s_waitcnt vmcnt(0)
	global_store_dword v65, v0, s[8:9] sc1
	s_branch .LBB0_140

; #define TID (opq_v((int)threadIdx.x))
; DEVINL void phase_mixers(const Ctx& c, int layer, unsigned char* lds) {
;     ...
;         const int nw = (G - 96) * (NTHR / 64), wid = (bx - 96) * (NTHR / 64) + (TID >> 6);
;         const int NSB = 68 * 64;
;         for (int i = wid; i < 2 * NSB; i += nw) {
;             if (i < NSB) { const int qg = 67 - i / 64, bh = i & 63; sb_task(c, bh >> 3, bh & 7, qg); }
;             else { const int i2 = i - NSB; const int qg = 67 - i2 / 64, bh = i2 & 63; swa_task(c, layer, bh >> 3, bh & 7, qg); }
.LBB0_240:
	s_waitcnt vmcnt(0)
	v_mov_b32_e32 v1, v160
	s_movk_i32 s0, 0x2200
	v_ashrrev_i32_e32 v0, 6, v1
	v_lshl_add_u32 v0, s95, 3, v0
	s_waitcnt vmcnt(0)
	v_add_u32_e32 v168, 0xfffffc00, v0
	v_cmp_gt_i32_e32 vcc, s0, v168
	s_and_saveexec_b64 s[22:23], vcc
	s_cbranch_execz .LBB0_265
	v_bfe_u32 v1, v1, 6, 3
	v_add_u32_e32 v2, 1, v1
	v_cvt_f32_ubyte0_e32 v2, v2
	v_exp_f32_e64 v3, -v2
	v_readlane_b32 s0, v245, 32
	v_readlane_b32 s1, v245, 33
	v_readlane_b32 s4, v245, 11
	v_lshl_or_b32 v2, s0, 3, v1
	v_readlane_b32 s0, v247, 43
	v_add_u32_e32 v169, 0xffffeb00, v0
	v_lshlrev_b32_e32 v0, 6, v1
	v_mul_f32_e32 v170, 0x3fb8aa3b, v3
	v_ashrrev_i32_e32 v3, 31, v2
	v_lshlrev_b32_e32 v64, 7, v1
	v_readlane_b32 s1, v247, 44
	v_readlane_b32 s12, v245, 19
	v_readlane_b32 s13, v245, 20
	v_lshl_add_u64 v[82:83], s[0:1], 0, v[64:65]
	s_mov_b64 s[50:51], 0
	v_lshl_add_u64 v[84:85], v[2:3], 2, s[12:13]
	v_lshlrev_b32_e32 v86, 1, v0
	v_readlane_b32 s5, v245, 12
	v_readlane_b32 s6, v245, 13
	v_readlane_b32 s7, v245, 14
	v_readlane_b32 s8, v245, 15
	v_readlane_b32 s9, v245, 16
	v_readlane_b32 s10, v245, 17
	v_readlane_b32 s11, v245, 18
	v_readlane_b32 s14, v245, 21
	v_readlane_b32 s15, v245, 22
	v_readlane_b32 s16, v245, 23
	v_readlane_b32 s17, v245, 24
	v_readlane_b32 s18, v245, 25
	v_readlane_b32 s19, v245, 26
	s_branch .LBB0_244

; DEVINL void phase_mixers(const Ctx& c, int layer, unsigned char* lds) {
;     ...
;         for (int i = wid; i < 2 * NSB; i += nw) {
;             if (i < NSB) { const int qg = 67 - i / 64, bh = i & 63; sb_task(c, bh >> 3, bh & 7, qg); }
;             else { const int i2 = i - NSB; const int qg = 67 - i2 / 64, bh = i2 & 63; swa_task(c, layer, bh >> 3, bh & 7, qg); }
;         }
.LBB0_243:
	s_or_b64 exec, exec, s[52:53]
	s_movk_i32 s1, 0x400
	s_movk_i32 s0, 0x21ff
	global_store_dwordx2 v[2:3], v[0:1], off offset:112
	v_add_u32_e32 v168, s1, v168
	v_cmp_lt_i32_e32 vcc, s0, v168
	s_or_b64 s[50:51], vcc, s[50:51]
	v_add_u32_e32 v169, s1, v169
	s_andn2_b64 exec, exec, s[50:51]
	s_cbranch_execz .LBB0_265

;     DEVINL bf16_t* BVT() const { return (bf16_t*)(ws + OFF_BVT); }
;     DEVINL bf16_t* BKT() const { return (bf16_t*)(ws + OFF_BKT); }
;     DEVINL bf16_t* Y() const { return (bf16_t*)(ws + OFF_Y); }
; #define TID (opq_v((int)threadIdx.x))
; DEVINL float fexp2(float x) { return __builtin_amdgcn_exp2f(x); }
; DEVINL float flog2(float x) { return __builtin_amdgcn_logf(x); }
; DEVINL void ret_block(const Ctx& c, int b, int hd, unsigned char* lds) {
;     bf16_t* ST = (bf16_t*)lds;
;     float* ssq = (float*)(lds + 128 * LROW);
;     const int tid = TID, lane = tid & 63, w = tid >> 6, r = lane & 31, h = lane >> 5;
;     const int qs = w & 3, dh = w >> 2, dvt = w >> 1, dt = w & 1;
;     const float lg2 = flog2(1.f - fexp2(-5.f - (float)hd));
;     const float gam = fexp2(lg2), gam128 = fexp2(lg2 * 128.f);
;     f32x16 sacc;
; #pragma unroll
;     for (int i = 0; i < 16; ++i) sacc[i] = 0.f;
;     const bf16_t* vtb = c.BVT() + (size_t)(b * 512 + hd * 128) * L;
;     const bf16_t* ktb = c.BKT() + (size_t)(b * 256 + hd * 64) * L;
;     bf16_t* Y = c.Y() + (size_t)T * 512;
;     for (int ch = 0; ch < L / 128; ++ch) {
.LBB0_266:
	s_and_b64 vcc, exec, s[0:1]
	s_cbranch_vccz .LBB0_275
	s_and_b32 s12, s95, 3
	s_waitcnt vmcnt(0)
	v_cvt_f32_ubyte0_e32 v0, s12
	v_sub_f32_e32 v0, 0xc0a00000, v0
	v_exp_f32_e32 v0, v0
	v_mov_b32_e32 v2, v160
	s_cmp_gt_u32 s95, 0x5f
	s_cselect_b32 s101, 1, 0
	s_cselect_b32 s100, 0x60, 64
	s_sub_i32 s0, s95, s100
	s_cmp_eq_u32 s101, 1
	s_cselect_b32 s100, 17, 9
	v_sub_f32_e32 v0, 1.0, v0
	v_log_f32_e32 v93, v0
	v_ashrrev_i32_e32 v0, 6, v2
	v_and_b32_e32 v6, 1, v0
	v_lshlrev_b32_e32 v0, 5, v0
	v_and_b32_e32 v3, 31, v2
	v_and_b32_e32 v10, 0x60, v0
	v_mul_f32_e32 v1, 0x43000000, v93
	v_or_b32_e32 v92, v10, v3
	v_exp_f32_e32 v88, v1
	v_lshlrev_b32_e32 v1, 6, v6
	v_lshlrev_b32_e32 v9, 1, v3
	v_cvt_f32_ubyte0_e32 v0, v92
	v_add3_u32 v9, 0, v1, v9
	v_mul_f32_e32 v0, v93, v0
	v_and_b32_e32 v1, 64, v162
	s_lshr_b32 s13, s0, 2
	v_ashrrev_i32_e32 v5, 8, v2
	s_lshl_b32 s14, s12, 7
	v_exp_f32_e32 v98, v0
	v_xor_b32_e32 v0, 32, v162
	v_add_u32_e32 v1, 64, v1
	s_lshl_b32 s4, s12, 8
	v_readlane_b32 s5, v247, 53
	v_bfe_u32 v4, v2, 5, 1
	v_ashrrev_i32_e32 v7, 2, v2
	v_lshlrev_b32_e32 v94, 6, v5
	v_cmp_lt_i32_e32 vcc, v0, v1
	s_add_u32 s4, s5, s4
	v_readlane_b32 s5, v247, 54
	v_and_b32_e32 v8, 0xffffffe0, v7
	v_lshlrev_b32_e32 v90, 2, v4
	v_cndmask_b32_e32 v0, v162, v0, vcc
	v_ashrrev_i32_e32 v95, 31, v94
	s_addc_u32 s5, s5, 0
	v_lshlrev_b32_e32 v64, 3, v4
	v_or_b32_e32 v11, v94, v3
	v_lshlrev_b32_e32 v96, 4, v4
	v_lshlrev_b32_e32 v122, 2, v0
	v_cmp_eq_u32_e64 s[0:1], 0, v4
	v_lshl_add_u64 v[0:1], v[94:95], 1, s[4:5]
	v_lshl_or_b32 v4, v6, 5, v3
	v_or_b32_e32 v6, v90, v8
	s_movk_i32 s4, 0x90
	v_mul_lo_u32 v6, v6, s4
	v_mul_lo_u32 v8, v11, s4
	s_add_u32 s4, s26, s14
	s_addc_u32 s5, s27, 0
	v_mov_b32_e32 v97, v65
	s_movk_i32 s15, 0x1100
	v_lshl_add_u64 v[104:105], s[4:5], 0, v[96:97]
	v_lshl_add_u64 v[106:107], v[0:1], 0, v[64:65]
	v_mad_i64_i32 v[0:1], s[4:5], v11, s15, 0
	s_mul_i32 s4, s13, 0x110000
	s_mul_i32 s5, s12, 0x44000
	s_add_i32 s66, s4, s5
	s_lshl_b64 s[4:5], s[66:67], 1
	v_readlane_b32 s8, v246, 26
	s_add_u32 s8, s8, s4
	v_readlane_b32 s9, v246, 29
	v_or_b32_e32 v0, v0, v64
	s_addc_u32 s9, s9, s5
	v_lshl_add_u64 v[108:109], s[8:9], 0, v[0:1]
	v_or_b32_e32 v0, 32, v11
	v_mad_i64_i32 v[0:1], s[10:11], v0, s15, 0
	v_or_b32_e32 v0, v0, v64
	v_lshl_add_u64 v[110:111], s[8:9], 0, v[0:1]
	s_movk_i32 s8, 0xffe0
	v_bfi_b32 v2, s8, v7, v2
	v_readlane_b32 s8, v246, 27
	v_readlane_b32 s9, v246, 28
	s_add_u32 s4, s8, s4
	s_addc_u32 s5, s9, s5
	v_mov_b64_e32 v[0:1], s[4:5]
	v_mad_i64_i32 v[112:113], s[4:5], v2, s15, v[0:1]
	s_mul_i32 s4, s13, 0x88000
	s_mul_i32 s12, s12, 0x22000
	v_exp_f32_e32 v86, v93
	s_add_i32 s66, s4, s12
	s_lshl_b64 s[4:5], s[66:67], 1
	v_mul_u32_u24_e32 v4, 0x880, v4
	s_add_u32 s4, s8, s4
	s_mul_i32 s6, s13, 0x880
	v_add_u32_e32 v12, 0, v96
	v_lshl_add_u32 v123, v92, 2, 0
	v_lshlrev_b32_e32 v5, 9, v5
	v_sub_u32_e32 v126, 0, v64
	v_lshlrev_b32_e32 v64, 1, v4
	s_addc_u32 s5, s9, s5
	v_mov_b32_e32 v0, 0
	s_mov_b32 s7, 0
	v_mov_b32_e32 v99, v98
	v_mov_b32_e32 v100, v86
	v_mov_b32_e32 v101, v86
	v_mov_b32_e32 v91, v92
	v_mov_b32_e32 v102, v88
	v_mov_b32_e32 v103, v88
	v_add_u32_e32 v124, 32, v10
	v_or_b32_e32 v125, s6, v3
	v_lshl_add_u64 v[114:115], s[4:5], 0, v[64:65]
	v_add_u32_e32 v127, v9, v6
	v_add_u32_e32 v128, v12, v8
	v_add_u32_e32 v129, v123, v5
	s_lshl_b32 s66, s14, 1
	v_mov_b32_e32 v1, v0
	v_mov_b32_e32 v2, v0
	v_mov_b32_e32 v3, v0
	v_mov_b32_e32 v4, v0
	v_mov_b32_e32 v5, v0
	v_mov_b32_e32 v6, v0
	v_mov_b32_e32 v7, v0
	v_mov_b32_e32 v8, v0
	v_mov_b32_e32 v9, v0
	v_mov_b32_e32 v10, v0
	v_mov_b32_e32 v11, v0
	v_mov_b32_e32 v12, v0
	v_mov_b32_e32 v13, v0
	v_mov_b32_e32 v14, v0
	v_mov_b32_e32 v15, v0
	v_lshlrev_b32_e32 v206, 1, v94
	v_add_u32_e32 v206, s14, v206
	v_lshlrev_b32_e32 v207, 1, v90
	v_sub_u32_e32 v206, v206, v207
	v_add_u32_e32 v206, 0x400, v206
	v_mov_b32_e32 v207, 0
	s_cmp_eq_u32 s101, 0
	s_cbranch_scc1 .LBB0_268
	v_mov_b32_e32 v89, v88
.Lret_pre:
	s_mov_b64 s[4:5], 0x15b40000
	v_lshl_add_u64 v[202:203], v[112:113], 0, v[96:97]
	v_lshl_add_u64 v[202:203], v[202:203], 0, s[4:5]
	s_mov_b64 s[4:5], 0x17080000
	v_lshl_add_u64 v[204:205], v[114:115], 0, v[96:97]
	v_lshl_add_u64 v[204:205], v[204:205], 0, s[4:5]
	global_load_dwordx4 v[132:135], v[202:203], off
	global_load_dwordx4 v[136:139], v[204:205], off
	global_load_dwordx4 v[140:143], v[202:203], off offset:32
	global_load_dwordx4 v[144:147], v[204:205], off offset:32
	global_load_dwordx4 v[148:151], v[202:203], off offset:64
	global_load_dwordx4 v[152:155], v[204:205], off offset:64
	global_load_dwordx4 v[156:159], v[202:203], off offset:96
	global_load_dwordx4 v[168:171], v[204:205], off offset:96
	global_load_dwordx4 v[172:175], v[202:203], off offset:128
	global_load_dwordx4 v[176:179], v[204:205], off offset:128
	global_load_dwordx4 v[180:183], v[202:203], off offset:160
	global_load_dwordx4 v[208:211], v[204:205], off offset:160
	global_load_dwordx4 v[212:215], v[202:203], off offset:192
	global_load_dwordx4 v[216:219], v[204:205], off offset:192
	global_load_dwordx4 v[220:223], v[202:203], off offset:224
	global_load_dwordx4 v[224:227], v[204:205], off offset:224
	v_pk_mul_f32 v[14:15], v[88:89], v[14:15]
	v_pk_mul_f32 v[12:13], v[88:89], v[12:13]
	v_pk_mul_f32 v[10:11], v[88:89], v[10:11]
	v_pk_mul_f32 v[8:9], v[88:89], v[8:9]
	v_pk_mul_f32 v[6:7], v[88:89], v[6:7]
	v_pk_mul_f32 v[4:5], v[88:89], v[4:5]
	v_pk_mul_f32 v[2:3], v[88:89], v[2:3]
	v_pk_mul_f32 v[0:1], v[88:89], v[0:1]
	s_waitcnt vmcnt(14)
; #define MFMA32(a, b, c) __builtin_amdgcn_mfma_f32_32x32x16_bf16((a), (b), (c), 0, 0, 0)
; DEVINL unsigned cvt_pk_bf16(float lo, float hi) { const f32x2 v = {lo, hi}; return __builtin_bit_cast(unsigned, __builtin_convertvector(v, bf16x2v)); }
; DEVINL float bflo(unsigned u) { return __uint_as_float(u << 16); }
; DEVINL float bfhi(unsigned u) { return __uint_as_float(u & 0xffff0000u); }
; DEVINL float fexp2(float x) { return __builtin_amdgcn_exp2f(x); }
; DEVINL void ret_block(const Ctx& c, int b, int hd, unsigned char* lds) {
;     ...
;         {
;             const bf16_t* va = vtb + (size_t)(dvt * 32 + r) * L + p0 + 8 * h;
;             const bf16_t* kb = ktb + (size_t)(dt * 32 + r) * L + p0 + 8 * h;
; #pragma unroll 2
;             for (int ks = 0; ks < 8; ++ks) {
;                 const bf16x8 vf = *(const bf16x8*)(va + 16 * ks);
;                 const u32x4 kr = *(const u32x4*)(kb + 16 * ks);
;                 u32x4 kd;
; #pragma unroll
;                 for (int jj = 0; jj < 4; ++jj) {
;                     const int j0 = 16 * ks + 8 * h + 2 * jj;
;                     kd[jj] = cvt_pk_bf16(bflo(kr[jj]) * fexp2(lg2 * (float)(127 - j0)), bfhi(kr[jj]) * fexp2(lg2 * (float)(126 - j0)));
;                 }
;                 sacc = MFMA32(vf, __builtin_bit_cast(bf16x8, kd), sacc);
;             }
	v_add_u32_e32 v32, 127, v126
	v_add_u32_e32 v33, 126, v126
	v_cvt_f32_u32_e32 v32, v32
	v_cvt_f32_u32_e32 v33, v33
	v_lshlrev_b32_e32 v34, 16, v136
	v_and_b32_e32 v35, 0xffff0000, v136
	v_mul_f32_e32 v32, v93, v32
	v_mul_f32_e32 v33, v93, v33
	v_exp_f32_e32 v32, v32
	v_exp_f32_e32 v33, v33
	s_nop 0
	v_pk_mul_f32 v[32:33], v[32:33], v[34:35]
	s_nop 0
	v_cvt_pk_bf16_f32 v136, v32, v33
	v_add_u32_e32 v32, 125, v126
	v_add_u32_e32 v33, 124, v126
	v_cvt_f32_u32_e32 v32, v32
	v_cvt_f32_u32_e32 v33, v33
	v_lshlrev_b32_e32 v34, 16, v137
	v_and_b32_e32 v35, 0xffff0000, v137
	v_mul_f32_e32 v32, v93, v32
	v_mul_f32_e32 v33, v93, v33
	v_exp_f32_e32 v32, v32
	v_exp_f32_e32 v33, v33
	s_nop 0
	v_pk_mul_f32 v[32:33], v[32:33], v[34:35]
	s_nop 0
	v_cvt_pk_bf16_f32 v137, v32, v33
	v_add_u32_e32 v32, 123, v126
	v_add_u32_e32 v33, 122, v126
	v_cvt_f32_u32_e32 v32, v32
	v_cvt_f32_u32_e32 v33, v33
	v_lshlrev_b32_e32 v34, 16, v138
	v_and_b32_e32 v35, 0xffff0000, v138
	v_mul_f32_e32 v32, v93, v32
	v_mul_f32_e32 v33, v93, v33
	v_exp_f32_e32 v32, v32
	v_exp_f32_e32 v33, v33
	s_nop 0
	v_pk_mul_f32 v[32:33], v[32:33], v[34:35]
	s_nop 0
	v_cvt_pk_bf16_f32 v138, v32, v33
	v_add_u32_e32 v32, 121, v126
	v_add_u32_e32 v33, 120, v126
	v_cvt_f32_u32_e32 v32, v32
	v_cvt_f32_u32_e32 v33, v33
	v_lshlrev_b32_e32 v34, 16, v139
	v_and_b32_e32 v35, 0xffff0000, v139
	v_mul_f32_e32 v32, v93, v32
	v_mul_f32_e32 v33, v93, v33
	v_exp_f32_e32 v32, v32
	v_exp_f32_e32 v33, v33
	s_nop 0
	v_pk_mul_f32 v[32:33], v[32:33], v[34:35]
	s_nop 0
	v_cvt_pk_bf16_f32 v139, v32, v33
	s_nop 1
	v_mfma_f32_32x32x16_bf16 v[0:15], v[132:135], v[136:139], v[0:15]
	s_waitcnt vmcnt(12)
	v_add_u32_e32 v32, 111, v126
	v_add_u32_e32 v33, 110, v126
	v_cvt_f32_u32_e32 v32, v32
	v_cvt_f32_u32_e32 v33, v33
	v_lshlrev_b32_e32 v34, 16, v144
	v_and_b32_e32 v35, 0xffff0000, v144
	v_mul_f32_e32 v32, v93, v32
	v_mul_f32_e32 v33, v93, v33
	v_exp_f32_e32 v32, v32
	v_exp_f32_e32 v33, v33
	s_nop 0
	v_pk_mul_f32 v[32:33], v[32:33], v[34:35]
	s_nop 0
	v_cvt_pk_bf16_f32 v144, v32, v33
	v_add_u32_e32 v32, 109, v126
	v_add_u32_e32 v33, 108, v126
	v_cvt_f32_u32_e32 v32, v32
	v_cvt_f32_u32_e32 v33, v33
	v_lshlrev_b32_e32 v34, 16, v145
	v_and_b32_e32 v35, 0xffff0000, v145
	v_mul_f32_e32 v32, v93, v32
	v_mul_f32_e32 v33, v93, v33
	v_exp_f32_e32 v32, v32
	v_exp_f32_e32 v33, v33
	s_nop 0
	v_pk_mul_f32 v[32:33], v[32:33], v[34:35]
	s_nop 0
	v_cvt_pk_bf16_f32 v145, v32, v33
	v_add_u32_e32 v32, 107, v126
	v_add_u32_e32 v33, 106, v126
	v_cvt_f32_u32_e32 v32, v32
	v_cvt_f32_u32_e32 v33, v33
	v_lshlrev_b32_e32 v34, 16, v146
	v_and_b32_e32 v35, 0xffff0000, v146
	v_mul_f32_e32 v32, v93, v32
	v_mul_f32_e32 v33, v93, v33
	v_exp_f32_e32 v32, v32
	v_exp_f32_e32 v33, v33
	s_nop 0
	v_pk_mul_f32 v[32:33], v[32:33], v[34:35]
	s_nop 0
	v_cvt_pk_bf16_f32 v146, v32, v33
	v_add_u32_e32 v32, 105, v126
	v_add_u32_e32 v33, 104, v126
	v_cvt_f32_u32_e32 v32, v32
	v_cvt_f32_u32_e32 v33, v33
	v_lshlrev_b32_e32 v34, 16, v147
	v_and_b32_e32 v35, 0xffff0000, v147
	v_mul_f32_e32 v32, v93, v32
	v_mul_f32_e32 v33, v93, v33
	v_exp_f32_e32 v32, v32
	v_exp_f32_e32 v33, v33
	s_nop 0
	v_pk_mul_f32 v[32:33], v[32:33], v[34:35]
	s_nop 0
	v_cvt_pk_bf16_f32 v147, v32, v33
	s_nop 1
	v_mfma_f32_32x32x16_bf16 v[0:15], v[140:143], v[144:147], v[0:15]
	s_waitcnt vmcnt(10)
	v_add_u32_e32 v32, 95, v126
	v_add_u32_e32 v33, 94, v126
	v_cvt_f32_u32_e32 v32, v32
	v_cvt_f32_u32_e32 v33, v33
	v_lshlrev_b32_e32 v34, 16, v152
	v_and_b32_e32 v35, 0xffff0000, v152
	v_mul_f32_e32 v32, v93, v32
	v_mul_f32_e32 v33, v93, v33
	v_exp_f32_e32 v32, v32
	v_exp_f32_e32 v33, v33
	s_nop 0
	v_pk_mul_f32 v[32:33], v[32:33], v[34:35]
	s_nop 0
	v_cvt_pk_bf16_f32 v152, v32, v33
	v_add_u32_e32 v32, 93, v126
	v_add_u32_e32 v33, 92, v126
	v_cvt_f32_u32_e32 v32, v32
	v_cvt_f32_u32_e32 v33, v33
	v_lshlrev_b32_e32 v34, 16, v153
	v_and_b32_e32 v35, 0xffff0000, v153
	v_mul_f32_e32 v32, v93, v32
	v_mul_f32_e32 v33, v93, v33
	v_exp_f32_e32 v32, v32
	v_exp_f32_e32 v33, v33
	s_nop 0
	v_pk_mul_f32 v[32:33], v[32:33], v[34:35]
	s_nop 0
	v_cvt_pk_bf16_f32 v153, v32, v33
	v_add_u32_e32 v32, 91, v126
	v_add_u32_e32 v33, 90, v126
	v_cvt_f32_u32_e32 v32, v32
	v_cvt_f32_u32_e32 v33, v33
	v_lshlrev_b32_e32 v34, 16, v154
	v_and_b32_e32 v35, 0xffff0000, v154
	v_mul_f32_e32 v32, v93, v32
	v_mul_f32_e32 v33, v93, v33
	v_exp_f32_e32 v32, v32
	v_exp_f32_e32 v33, v33
	s_nop 0
	v_pk_mul_f32 v[32:33], v[32:33], v[34:35]
	s_nop 0
	v_cvt_pk_bf16_f32 v154, v32, v33
	v_add_u32_e32 v32, 89, v126
	v_add_u32_e32 v33, 88, v126
	v_cvt_f32_u32_e32 v32, v32
	v_cvt_f32_u32_e32 v33, v33
	v_lshlrev_b32_e32 v34, 16, v155
	v_and_b32_e32 v35, 0xffff0000, v155
	v_mul_f32_e32 v32, v93, v32
	v_mul_f32_e32 v33, v93, v33
	v_exp_f32_e32 v32, v32
	v_exp_f32_e32 v33, v33
	s_nop 0
	v_pk_mul_f32 v[32:33], v[32:33], v[34:35]
	s_nop 0
	v_cvt_pk_bf16_f32 v155, v32, v33
	s_nop 1
	v_mfma_f32_32x32x16_bf16 v[0:15], v[148:151], v[152:155], v[0:15]
	s_waitcnt vmcnt(8)
; #define MFMA32(a, b, c) __builtin_amdgcn_mfma_f32_32x32x16_bf16((a), (b), (c), 0, 0, 0)
; DEVINL unsigned cvt_pk_bf16(float lo, float hi) { const f32x2 v = {lo, hi}; return __builtin_bit_cast(unsigned, __builtin_convertvector(v, bf16x2v)); }
; DEVINL float bflo(unsigned u) { return __uint_as_float(u << 16); }
; DEVINL float bfhi(unsigned u) { return __uint_as_float(u & 0xffff0000u); }
; DEVINL float fexp2(float x) { return __builtin_amdgcn_exp2f(x); }
; DEVINL void ret_block(const Ctx& c, int b, int hd, unsigned char* lds) {
;     ...
;         {
;             const bf16_t* va = vtb + (size_t)(dvt * 32 + r) * L + p0 + 8 * h;
;             const bf16_t* kb = ktb + (size_t)(dt * 32 + r) * L + p0 + 8 * h;
; #pragma unroll 2
;             for (int ks = 0; ks < 8; ++ks) {
;                 const bf16x8 vf = *(const bf16x8*)(va + 16 * ks);
;                 const u32x4 kr = *(const u32x4*)(kb + 16 * ks);
;                 u32x4 kd;
; #pragma unroll
;                 for (int jj = 0; jj < 4; ++jj) {
;                     const int j0 = 16 * ks + 8 * h + 2 * jj;
;                     kd[jj] = cvt_pk_bf16(bflo(kr[jj]) * fexp2(lg2 * (float)(127 - j0)), bfhi(kr[jj]) * fexp2(lg2 * (float)(126 - j0)));
;                 }
;                 sacc = MFMA32(vf, __builtin_bit_cast(bf16x8, kd), sacc);
;             }
	v_add_u32_e32 v32, 79, v126
	v_add_u32_e32 v33, 78, v126
	v_cvt_f32_u32_e32 v32, v32
	v_cvt_f32_u32_e32 v33, v33
	v_lshlrev_b32_e32 v34, 16, v168
	v_and_b32_e32 v35, 0xffff0000, v168
	v_mul_f32_e32 v32, v93, v32
	v_mul_f32_e32 v33, v93, v33
	v_exp_f32_e32 v32, v32
	v_exp_f32_e32 v33, v33
	s_nop 0
	v_pk_mul_f32 v[32:33], v[32:33], v[34:35]
	s_nop 0
	v_cvt_pk_bf16_f32 v168, v32, v33
	v_add_u32_e32 v32, 77, v126
	v_add_u32_e32 v33, 76, v126
	v_cvt_f32_u32_e32 v32, v32
	v_cvt_f32_u32_e32 v33, v33
	v_lshlrev_b32_e32 v34, 16, v169
	v_and_b32_e32 v35, 0xffff0000, v169
	v_mul_f32_e32 v32, v93, v32
	v_mul_f32_e32 v33, v93, v33
	v_exp_f32_e32 v32, v32
	v_exp_f32_e32 v33, v33
	s_nop 0
	v_pk_mul_f32 v[32:33], v[32:33], v[34:35]
	s_nop 0
	v_cvt_pk_bf16_f32 v169, v32, v33
	v_add_u32_e32 v32, 75, v126
	v_add_u32_e32 v33, 74, v126
	v_cvt_f32_u32_e32 v32, v32
	v_cvt_f32_u32_e32 v33, v33
	v_lshlrev_b32_e32 v34, 16, v170
	v_and_b32_e32 v35, 0xffff0000, v170
	v_mul_f32_e32 v32, v93, v32
	v_mul_f32_e32 v33, v93, v33
	v_exp_f32_e32 v32, v32
	v_exp_f32_e32 v33, v33
	s_nop 0
	v_pk_mul_f32 v[32:33], v[32:33], v[34:35]
	s_nop 0
	v_cvt_pk_bf16_f32 v170, v32, v33
	v_add_u32_e32 v32, 73, v126
	v_add_u32_e32 v33, 72, v126
	v_cvt_f32_u32_e32 v32, v32
	v_cvt_f32_u32_e32 v33, v33
	v_lshlrev_b32_e32 v34, 16, v171
	v_and_b32_e32 v35, 0xffff0000, v171
	v_mul_f32_e32 v32, v93, v32
	v_mul_f32_e32 v33, v93, v33
	v_exp_f32_e32 v32, v32
	v_exp_f32_e32 v33, v33
	s_nop 0
	v_pk_mul_f32 v[32:33], v[32:33], v[34:35]
	s_nop 0
	v_cvt_pk_bf16_f32 v171, v32, v33
	s_nop 1
	v_mfma_f32_32x32x16_bf16 v[0:15], v[156:159], v[168:171], v[0:15]
	s_waitcnt vmcnt(6)
	v_add_u32_e32 v32, 63, v126
	v_add_u32_e32 v33, 62, v126
	v_cvt_f32_u32_e32 v32, v32
	v_cvt_f32_u32_e32 v33, v33
	v_lshlrev_b32_e32 v34, 16, v176
	v_and_b32_e32 v35, 0xffff0000, v176
	v_mul_f32_e32 v32, v93, v32
	v_mul_f32_e32 v33, v93, v33
	v_exp_f32_e32 v32, v32
	v_exp_f32_e32 v33, v33
	s_nop 0
	v_pk_mul_f32 v[32:33], v[32:33], v[34:35]
	s_nop 0
	v_cvt_pk_bf16_f32 v176, v32, v33
	v_add_u32_e32 v32, 61, v126
	v_add_u32_e32 v33, 60, v126
	v_cvt_f32_u32_e32 v32, v32
	v_cvt_f32_u32_e32 v33, v33
	v_lshlrev_b32_e32 v34, 16, v177
	v_and_b32_e32 v35, 0xffff0000, v177
	v_mul_f32_e32 v32, v93, v32
	v_mul_f32_e32 v33, v93, v33
	v_exp_f32_e32 v32, v32
	v_exp_f32_e32 v33, v33
	s_nop 0
	v_pk_mul_f32 v[32:33], v[32:33], v[34:35]
	s_nop 0
	v_cvt_pk_bf16_f32 v177, v32, v33
	v_add_u32_e32 v32, 59, v126
	v_add_u32_e32 v33, 58, v126
	v_cvt_f32_u32_e32 v32, v32
	v_cvt_f32_u32_e32 v33, v33
	v_lshlrev_b32_e32 v34, 16, v178
	v_and_b32_e32 v35, 0xffff0000, v178
	v_mul_f32_e32 v32, v93, v32
	v_mul_f32_e32 v33, v93, v33
	v_exp_f32_e32 v32, v32
	v_exp_f32_e32 v33, v33
	s_nop 0
	v_pk_mul_f32 v[32:33], v[32:33], v[34:35]
	s_nop 0
	v_cvt_pk_bf16_f32 v178, v32, v33
	v_add_u32_e32 v32, 57, v126
	v_add_u32_e32 v33, 56, v126
	v_cvt_f32_u32_e32 v32, v32
	v_cvt_f32_u32_e32 v33, v33
	v_lshlrev_b32_e32 v34, 16, v179
	v_and_b32_e32 v35, 0xffff0000, v179
	v_mul_f32_e32 v32, v93, v32
	v_mul_f32_e32 v33, v93, v33
	v_exp_f32_e32 v32, v32
	v_exp_f32_e32 v33, v33
	s_nop 0
	v_pk_mul_f32 v[32:33], v[32:33], v[34:35]
	s_nop 0
	v_cvt_pk_bf16_f32 v179, v32, v33
	s_nop 1
	v_mfma_f32_32x32x16_bf16 v[0:15], v[172:175], v[176:179], v[0:15]
	s_waitcnt vmcnt(4)
	v_add_u32_e32 v32, 47, v126
	v_add_u32_e32 v33, 46, v126
	v_cvt_f32_u32_e32 v32, v32
	v_cvt_f32_u32_e32 v33, v33
	v_lshlrev_b32_e32 v34, 16, v208
	v_and_b32_e32 v35, 0xffff0000, v208
	v_mul_f32_e32 v32, v93, v32
	v_mul_f32_e32 v33, v93, v33
	v_exp_f32_e32 v32, v32
	v_exp_f32_e32 v33, v33
	s_nop 0
	v_pk_mul_f32 v[32:33], v[32:33], v[34:35]
	s_nop 0
	v_cvt_pk_bf16_f32 v208, v32, v33
	v_add_u32_e32 v32, 45, v126
	v_add_u32_e32 v33, 44, v126
	v_cvt_f32_u32_e32 v32, v32
	v_cvt_f32_u32_e32 v33, v33
	v_lshlrev_b32_e32 v34, 16, v209
	v_and_b32_e32 v35, 0xffff0000, v209
	v_mul_f32_e32 v32, v93, v32
	v_mul_f32_e32 v33, v93, v33
	v_exp_f32_e32 v32, v32
	v_exp_f32_e32 v33, v33
	s_nop 0
	v_pk_mul_f32 v[32:33], v[32:33], v[34:35]
	s_nop 0
	v_cvt_pk_bf16_f32 v209, v32, v33
	v_add_u32_e32 v32, 43, v126
	v_add_u32_e32 v33, 42, v126
	v_cvt_f32_u32_e32 v32, v32
	v_cvt_f32_u32_e32 v33, v33
	v_lshlrev_b32_e32 v34, 16, v210
	v_and_b32_e32 v35, 0xffff0000, v210
	v_mul_f32_e32 v32, v93, v32
	v_mul_f32_e32 v33, v93, v33
	v_exp_f32_e32 v32, v32
	v_exp_f32_e32 v33, v33
	s_nop 0
	v_pk_mul_f32 v[32:33], v[32:33], v[34:35]
	s_nop 0
	v_cvt_pk_bf16_f32 v210, v32, v33
	v_add_u32_e32 v32, 41, v126
	v_add_u32_e32 v33, 40, v126
	v_cvt_f32_u32_e32 v32, v32
	v_cvt_f32_u32_e32 v33, v33
	v_lshlrev_b32_e32 v34, 16, v211
	v_and_b32_e32 v35, 0xffff0000, v211
	v_mul_f32_e32 v32, v93, v32
	v_mul_f32_e32 v33, v93, v33
	v_exp_f32_e32 v32, v32
	v_exp_f32_e32 v33, v33
	s_nop 0
	v_pk_mul_f32 v[32:33], v[32:33], v[34:35]
	s_nop 0
	v_cvt_pk_bf16_f32 v211, v32, v33
	s_nop 1
	v_mfma_f32_32x32x16_bf16 v[0:15], v[180:183], v[208:211], v[0:15]
	s_waitcnt vmcnt(2)
; #define MFMA32(a, b, c) __builtin_amdgcn_mfma_f32_32x32x16_bf16((a), (b), (c), 0, 0, 0)
; DEVINL unsigned cvt_pk_bf16(float lo, float hi) { const f32x2 v = {lo, hi}; return __builtin_bit_cast(unsigned, __builtin_convertvector(v, bf16x2v)); }
; DEVINL float bflo(unsigned u) { return __uint_as_float(u << 16); }
; DEVINL float bfhi(unsigned u) { return __uint_as_float(u & 0xffff0000u); }
; DEVINL float fexp2(float x) { return __builtin_amdgcn_exp2f(x); }
; DEVINL void ret_block(const Ctx& c, int b, int hd, unsigned char* lds) {
;     ...
;         {
;             const bf16_t* va = vtb + (size_t)(dvt * 32 + r) * L + p0 + 8 * h;
;             const bf16_t* kb = ktb + (size_t)(dt * 32 + r) * L + p0 + 8 * h;
; #pragma unroll 2
;             for (int ks = 0; ks < 8; ++ks) {
;                 const bf16x8 vf = *(const bf16x8*)(va + 16 * ks);
;                 const u32x4 kr = *(const u32x4*)(kb + 16 * ks);
;                 u32x4 kd;
; #pragma unroll
;                 for (int jj = 0; jj < 4; ++jj) {
;                     const int j0 = 16 * ks + 8 * h + 2 * jj;
;                     kd[jj] = cvt_pk_bf16(bflo(kr[jj]) * fexp2(lg2 * (float)(127 - j0)), bfhi(kr[jj]) * fexp2(lg2 * (float)(126 - j0)));
;                 }
;                 sacc = MFMA32(vf, __builtin_bit_cast(bf16x8, kd), sacc);
;             }
	v_add_u32_e32 v32, 31, v126
	v_add_u32_e32 v33, 30, v126
	v_cvt_f32_u32_e32 v32, v32
	v_cvt_f32_u32_e32 v33, v33
	v_lshlrev_b32_e32 v34, 16, v216
	v_and_b32_e32 v35, 0xffff0000, v216
	v_mul_f32_e32 v32, v93, v32
	v_mul_f32_e32 v33, v93, v33
	v_exp_f32_e32 v32, v32
	v_exp_f32_e32 v33, v33
	s_nop 0
	v_pk_mul_f32 v[32:33], v[32:33], v[34:35]
	s_nop 0
	v_cvt_pk_bf16_f32 v216, v32, v33
	v_add_u32_e32 v32, 29, v126
	v_add_u32_e32 v33, 28, v126
	v_cvt_f32_u32_e32 v32, v32
	v_cvt_f32_u32_e32 v33, v33
	v_lshlrev_b32_e32 v34, 16, v217
	v_and_b32_e32 v35, 0xffff0000, v217
	v_mul_f32_e32 v32, v93, v32
	v_mul_f32_e32 v33, v93, v33
	v_exp_f32_e32 v32, v32
	v_exp_f32_e32 v33, v33
	s_nop 0
	v_pk_mul_f32 v[32:33], v[32:33], v[34:35]
	s_nop 0
	v_cvt_pk_bf16_f32 v217, v32, v33
	v_add_u32_e32 v32, 27, v126
	v_add_u32_e32 v33, 26, v126
	v_cvt_f32_u32_e32 v32, v32
	v_cvt_f32_u32_e32 v33, v33
	v_lshlrev_b32_e32 v34, 16, v218
	v_and_b32_e32 v35, 0xffff0000, v218
	v_mul_f32_e32 v32, v93, v32
	v_mul_f32_e32 v33, v93, v33
	v_exp_f32_e32 v32, v32
	v_exp_f32_e32 v33, v33
	s_nop 0
	v_pk_mul_f32 v[32:33], v[32:33], v[34:35]
	s_nop 0
	v_cvt_pk_bf16_f32 v218, v32, v33
	v_add_u32_e32 v32, 25, v126
	v_add_u32_e32 v33, 24, v126
	v_cvt_f32_u32_e32 v32, v32
	v_cvt_f32_u32_e32 v33, v33
	v_lshlrev_b32_e32 v34, 16, v219
	v_and_b32_e32 v35, 0xffff0000, v219
	v_mul_f32_e32 v32, v93, v32
	v_mul_f32_e32 v33, v93, v33
	v_exp_f32_e32 v32, v32
	v_exp_f32_e32 v33, v33
	s_nop 0
	v_pk_mul_f32 v[32:33], v[32:33], v[34:35]
	s_nop 0
	v_cvt_pk_bf16_f32 v219, v32, v33
	s_nop 1
	v_mfma_f32_32x32x16_bf16 v[0:15], v[212:215], v[216:219], v[0:15]
	s_waitcnt vmcnt(0)
	v_add_u32_e32 v32, 15, v126
	v_add_u32_e32 v33, 14, v126
	v_cvt_f32_u32_e32 v32, v32
	v_cvt_f32_u32_e32 v33, v33
	v_lshlrev_b32_e32 v34, 16, v224
	v_and_b32_e32 v35, 0xffff0000, v224
	v_mul_f32_e32 v32, v93, v32
	v_mul_f32_e32 v33, v93, v33
	v_exp_f32_e32 v32, v32
	v_exp_f32_e32 v33, v33
	s_nop 0
	v_pk_mul_f32 v[32:33], v[32:33], v[34:35]
	s_nop 0
	v_cvt_pk_bf16_f32 v224, v32, v33
	v_add_u32_e32 v32, 13, v126
	v_add_u32_e32 v33, 12, v126
	v_cvt_f32_u32_e32 v32, v32
	v_cvt_f32_u32_e32 v33, v33
	v_lshlrev_b32_e32 v34, 16, v225
	v_and_b32_e32 v35, 0xffff0000, v225
	v_mul_f32_e32 v32, v93, v32
	v_mul_f32_e32 v33, v93, v33
	v_exp_f32_e32 v32, v32
	v_exp_f32_e32 v33, v33
	s_nop 0
	v_pk_mul_f32 v[32:33], v[32:33], v[34:35]
	s_nop 0
	v_cvt_pk_bf16_f32 v225, v32, v33
	v_add_u32_e32 v32, 11, v126
	v_add_u32_e32 v33, 10, v126
	v_cvt_f32_u32_e32 v32, v32
	v_cvt_f32_u32_e32 v33, v33
	v_lshlrev_b32_e32 v34, 16, v226
	v_and_b32_e32 v35, 0xffff0000, v226
	v_mul_f32_e32 v32, v93, v32
	v_mul_f32_e32 v33, v93, v33
	v_exp_f32_e32 v32, v32
	v_exp_f32_e32 v33, v33
	s_nop 0
	v_pk_mul_f32 v[32:33], v[32:33], v[34:35]
	s_nop 0
	v_cvt_pk_bf16_f32 v226, v32, v33
	v_add_u32_e32 v32, 9, v126
	v_add_u32_e32 v33, 8, v126
	v_cvt_f32_u32_e32 v32, v32
	v_cvt_f32_u32_e32 v33, v33
	v_lshlrev_b32_e32 v34, 16, v227
	v_and_b32_e32 v35, 0xffff0000, v227
	v_mul_f32_e32 v32, v93, v32
	v_mul_f32_e32 v33, v93, v33
	v_exp_f32_e32 v32, v32
	v_exp_f32_e32 v33, v33
	s_nop 0
	v_pk_mul_f32 v[32:33], v[32:33], v[34:35]
	s_nop 0
	v_cvt_pk_bf16_f32 v227, v32, v33
	s_nop 1
	v_mfma_f32_32x32x16_bf16 v[0:15], v[220:223], v[224:227], v[0:15]
	s_add_i32 s7, s7, 1
	v_add_u32_e32 v125, 0x80, v125
	v_lshl_add_u64 v[108:109], v[108:109], 0, s[84:85]
	v_lshl_add_u64 v[110:111], v[110:111], 0, s[84:85]
	v_lshl_add_u64 v[112:113], v[112:113], 0, s[84:85]
	v_lshl_add_u64 v[114:115], v[114:115], 0, s[84:85]
	s_cmp_eq_u32 s7, 9
	s_cbranch_scc0 .Lret_pre

;     DEVINL bf16_t* Z() const { return (bf16_t*)(ws + OFF_Z); }
;     DEVINL bf16_t* Y() const { return (bf16_t*)(ws + OFF_Y); }
; DEVINL unsigned cvt_pk_bf16(float lo, float hi) { const f32x2 v = {lo, hi}; return __builtin_bit_cast(unsigned, __builtin_convertvector(v, bf16x2v)); }
; DEVINL float bflo(unsigned u) { return __uint_as_float(u << 16); }
; DEVINL float bfhi(unsigned u) { return __uint_as_float(u & 0xffff0000u); }
; DEVINL float fexp2(float x) { return __builtin_amdgcn_exp2f(x); }
; DEVINL float sigmoidf_(float x) { return __builtin_amdgcn_rcpf(1.f + fexp2(-x * LOG2E)); }
; DEVINL void ret_block(const Ctx& c, int b, int hd, unsigned char* lds) {
;     ...
;         const float gq = fexp2(lg2 * (float)ql);
;         float ss = 0.f;
; #pragma unroll
;         for (int d = 0; d < 2; ++d)
; #pragma unroll
;             for (int i = 0; i < 16; ++i) { o[d][i] *= gq; ss += o[d][i] * o[d][i]; }
;         ss += __shfl_xor(ss, 32);
;         if (h == 0) ssq[dh * 128 + ql] = ss;
;         __syncthreads();
;         const float rs = rsqrtf((ssq[ql] + ssq[128 + ql]) * (1.f / 128.f) + 1e-6f);
;         {
;             const bf16_t* gp = c.Z() + (size_t)(t0 + ql) * ZW + Z_BG + hd * 128 + dh * 64;
;             bf16_t* yp = Y + (size_t)(t0 + ql) * 512 + hd * 128 + dh * 64;
; #pragma unroll
;             for (int d = 0; d < 2; ++d)
; #pragma unroll
;                 for (int g = 0; g < 4; ++g) {
;                     const int dl = d * 32 + 8 * g + 4 * h;
;                     const u32x2 gg = *(const u32x2*)(gp + dl);
;                     float gv[4] = {bflo(gg[0]), bfhi(gg[0]), bflo(gg[1]), bfhi(gg[1])};
;                     float ov[4];
; #pragma unroll
;                     for (int j = 0; j < 4; ++j) { const float sg = gv[j] * sigmoidf_(gv[j]); ov[j] = sg * o[d][4 * g + j] * rs; }
;                     u32x2 pk; pk[0] = cvt_pk_bf16(ov[0], ov[1]); pk[1] = cvt_pk_bf16(ov[2], ov[3]);
;                     *(u32x2*)(yp + dl) = pk;
;                 }
;         }
; #pragma unroll
;         for (int i = 0; i < 16; ++i) sacc[i] *= gam128;
.LBB0_272:
	s_or_b64 exec, exec, s[4:5]
	s_waitcnt lgkmcnt(0)
	s_barrier
	ds_read2st64_b32 v[18:19], v123 offset0:72 offset1:74
	s_mov_b32 s4, 0x800000
	v_lshlrev_b64 v[28:29], 10, v[64:65]
	v_lshlrev_b32_e32 v64, 1, v90
	v_mov_b32_e32 v89, v88
	s_waitcnt lgkmcnt(0)
	v_add_f32_e32 v18, v18, v19
	v_fmamk_f32 v18, v18, 0x3c000000, v161
	v_cmp_gt_f32_e32 vcc, s4, v18
	v_mul_f32_e32 v19, 0x4b800000, v18
	v_readlane_b32 s4, v246, 27
	v_cndmask_b32_e32 v18, v18, v19, vcc
	v_readlane_b32 s5, v246, 28
	v_rsq_f32_e32 v18, v18
	v_pk_mul_f32 v[14:15], v[88:89], v[14:15]
	v_lshl_add_u64 v[22:23], v[116:117], 1, s[4:5]
	v_lshl_add_u64 v[22:23], v[22:23], 0, s[66:67]
	v_lshl_add_u64 v[22:23], v[94:95], 1, v[22:23]
	v_lshl_add_u64 v[22:23], v[22:23], 0, v[64:65]
	s_mov_b64 s[4:5], 0x2940c00
	v_mul_f32_e32 v19, 0x45800000, v18
	v_lshl_add_u64 v[24:25], v[22:23], 0, s[4:5]
	s_mov_b32 s4, 0x2940000
	v_cndmask_b32_e32 v18, v18, v19, vcc
	v_add_co_u32_e32 v22, vcc, s4, v22
	s_mov_b32 s4, 0
	s_nop 0
	v_addc_co_u32_e32 v23, vcc, 0, v23, vcc
	v_mov_b64_e32 v[22:23], v[186:187]
	v_pk_mul_f32 v[12:13], v[88:89], v[12:13]
	v_pk_mul_f32 v[10:11], v[88:89], v[10:11]
	v_pk_mul_f32 v[8:9], v[88:89], v[8:9]
	v_pk_mul_f32 v[6:7], v[88:89], v[6:7]
	v_pk_mul_f32 v[4:5], v[88:89], v[4:5]
	v_pk_mul_f32 v[2:3], v[88:89], v[2:3]
	v_pk_mul_f32 v[0:1], v[102:103], v[0:1]
	v_lshlrev_b32_e32 v30, 16, v22
	v_mul_f32_e32 v19, 0xbfb8aa3b, v30
	v_exp_f32_e32 v19, v19
	v_and_b32_e32 v31, 0xffff0000, v22
	v_lshlrev_b32_e32 v22, 16, v23
	v_and_b32_e32 v23, 0xffff0000, v23
	v_add_f32_e32 v19, 1.0, v19
	v_rcp_f32_e32 v46, v19
	v_mul_f32_e32 v19, 0xbfb8aa3b, v31
	v_exp_f32_e32 v19, v19
	s_nop 0
	v_add_f32_e32 v19, 1.0, v19
	v_rcp_f32_e32 v47, v19
	s_nop 0
	v_pk_mul_f32 v[30:31], v[46:47], v[30:31]
	s_nop 0
	v_pk_mul_f32 v[30:31], v[58:59], v[30:31]
	s_nop 0
	v_pk_mul_f32 v[30:31], v[18:19], v[30:31] op_sel_hi:[0,1]
	v_mul_f32_e32 v19, 0xbfb8aa3b, v22
	v_exp_f32_e32 v19, v19
	v_cvt_pk_bf16_f32 v30, v30, v31
	v_add_f32_e32 v19, 1.0, v19
	v_rcp_f32_e32 v46, v19
	v_mul_f32_e32 v19, 0xbfb8aa3b, v23
	v_exp_f32_e32 v19, v19
	s_nop 0
	v_add_f32_e32 v19, 1.0, v19
	v_rcp_f32_e32 v47, v19
	s_nop 0
	v_pk_mul_f32 v[22:23], v[46:47], v[22:23]
	s_nop 0
	v_pk_mul_f32 v[22:23], v[56:57], v[22:23]
	s_nop 0
	v_pk_mul_f32 v[22:23], v[18:19], v[22:23] op_sel_hi:[0,1]
	v_cvt_pk_bf16_f32 v31, v22, v23
	v_lshl_add_u64 v[22:23], v[106:107], 0, v[28:29]
	v_mov_b64_e32 v[28:29], v[188:189]
	s_nop 0
	global_store_dwordx2 v[22:23], v[30:31], off
	v_lshlrev_b32_e32 v30, 16, v28
	v_mul_f32_e32 v19, 0xbfb8aa3b, v30
	v_exp_f32_e32 v19, v19
	v_and_b32_e32 v31, 0xffff0000, v28
	v_lshlrev_b32_e32 v28, 16, v29
	v_and_b32_e32 v29, 0xffff0000, v29
	v_add_f32_e32 v19, 1.0, v19
	v_rcp_f32_e32 v46, v19
	v_mul_f32_e32 v19, 0xbfb8aa3b, v31
	v_exp_f32_e32 v19, v19
	s_nop 0
	v_add_f32_e32 v19, 1.0, v19
	v_rcp_f32_e32 v47, v19
	s_nop 0
	v_pk_mul_f32 v[30:31], v[46:47], v[30:31]
	s_nop 0
	v_pk_mul_f32 v[30:31], v[54:55], v[30:31]
	s_nop 0
	v_pk_mul_f32 v[30:31], v[18:19], v[30:31] op_sel_hi:[0,1]
	v_mul_f32_e32 v19, 0xbfb8aa3b, v28
	v_exp_f32_e32 v19, v19
	v_cvt_pk_bf16_f32 v30, v30, v31
	v_add_f32_e32 v19, 1.0, v19
	v_rcp_f32_e32 v46, v19
	v_mul_f32_e32 v19, 0xbfb8aa3b, v29
	v_exp_f32_e32 v19, v19
	s_nop 0
	v_add_f32_e32 v19, 1.0, v19
	v_rcp_f32_e32 v47, v19
	s_nop 0
	v_pk_mul_f32 v[28:29], v[46:47], v[28:29]
	s_nop 0
	v_pk_mul_f32 v[28:29], v[52:53], v[28:29]
	s_nop 0
	v_pk_mul_f32 v[28:29], v[18:19], v[28:29] op_sel_hi:[0,1]
	v_cvt_pk_bf16_f32 v31, v28, v29
	v_mov_b64_e32 v[28:29], v[190:191]
	s_nop 0
	global_store_dwordx2 v[22:23], v[30:31], off offset:16
	v_lshlrev_b32_e32 v30, 16, v28
	v_mul_f32_e32 v19, 0xbfb8aa3b, v30
	v_exp_f32_e32 v19, v19
	v_and_b32_e32 v31, 0xffff0000, v28
	v_lshlrev_b32_e32 v28, 16, v29
	v_and_b32_e32 v29, 0xffff0000, v29
	v_add_f32_e32 v19, 1.0, v19
	v_rcp_f32_e32 v46, v19
	v_mul_f32_e32 v19, 0xbfb8aa3b, v31
	v_exp_f32_e32 v19, v19
	s_nop 0
	v_add_f32_e32 v19, 1.0, v19
	v_rcp_f32_e32 v47, v19
	s_nop 0
	v_pk_mul_f32 v[30:31], v[46:47], v[30:31]
	s_nop 0
	v_pk_mul_f32 v[30:31], v[50:51], v[30:31]
	s_nop 0
	v_pk_mul_f32 v[30:31], v[18:19], v[30:31] op_sel_hi:[0,1]
	v_mul_f32_e32 v19, 0xbfb8aa3b, v28
	v_exp_f32_e32 v19, v19
	v_cvt_pk_bf16_f32 v30, v30, v31
	v_add_f32_e32 v19, 1.0, v19
	v_rcp_f32_e32 v46, v19
	v_mul_f32_e32 v19, 0xbfb8aa3b, v29
	v_exp_f32_e32 v19, v19
	s_nop 0
	v_add_f32_e32 v19, 1.0, v19
	v_rcp_f32_e32 v47, v19
	s_nop 0
	v_pk_mul_f32 v[28:29], v[46:47], v[28:29]
	s_nop 0
	v_pk_mul_f32 v[28:29], v[48:49], v[28:29]
	s_nop 0
	v_pk_mul_f32 v[28:29], v[18:19], v[28:29] op_sel_hi:[0,1]
	v_cvt_pk_bf16_f32 v31, v28, v29
	v_mov_b64_e32 v[28:29], v[192:193]
	s_nop 0
	global_store_dwordx2 v[22:23], v[30:31], off offset:32
	v_lshlrev_b32_e32 v30, 16, v28
	v_mul_f32_e32 v19, 0xbfb8aa3b, v30
	v_exp_f32_e32 v19, v19
	v_and_b32_e32 v31, 0xffff0000, v28
	v_lshlrev_b32_e32 v28, 16, v29
	v_and_b32_e32 v29, 0xffff0000, v29
	v_add_f32_e32 v19, 1.0, v19
	v_rcp_f32_e32 v46, v19
	v_mul_f32_e32 v19, 0xbfb8aa3b, v31
	v_exp_f32_e32 v19, v19
	s_nop 0
	v_add_f32_e32 v19, 1.0, v19
	v_rcp_f32_e32 v47, v19
	s_nop 0
	v_pk_mul_f32 v[30:31], v[46:47], v[30:31]
	s_nop 0
	v_pk_mul_f32 v[30:31], v[44:45], v[30:31]
	s_nop 0
	v_pk_mul_f32 v[30:31], v[18:19], v[30:31] op_sel_hi:[0,1]
	v_mul_f32_e32 v19, 0xbfb8aa3b, v28
	v_exp_f32_e32 v19, v19
	v_cvt_pk_bf16_f32 v30, v30, v31
	v_add_f32_e32 v19, 1.0, v19
	v_rcp_f32_e32 v44, v19
	v_mul_f32_e32 v19, 0xbfb8aa3b, v29
	v_exp_f32_e32 v19, v19
	s_nop 0
	v_add_f32_e32 v19, 1.0, v19
	v_rcp_f32_e32 v45, v19
	s_nop 0
	v_pk_mul_f32 v[28:29], v[44:45], v[28:29]
	s_nop 0
	v_pk_mul_f32 v[28:29], v[42:43], v[28:29]
; #define MFMA32(a, b, c) __builtin_amdgcn_mfma_f32_32x32x16_bf16((a), (b), (c), 0, 0, 0)
;     DEVINL bf16_t* Z() const { return (bf16_t*)(ws + OFF_Z); }
;     DEVINL bf16_t* Y() const { return (bf16_t*)(ws + OFF_Y); }
; DEVINL unsigned cvt_pk_bf16(float lo, float hi) { const f32x2 v = {lo, hi}; return __builtin_bit_cast(unsigned, __builtin_convertvector(v, bf16x2v)); }
; DEVINL float bflo(unsigned u) { return __uint_as_float(u << 16); }
; DEVINL float bfhi(unsigned u) { return __uint_as_float(u & 0xffff0000u); }
; DEVINL void ret_block(const Ctx& c, int b, int hd, unsigned char* lds) {
;     ...
;         {
;             const bf16_t* gp = c.Z() + (size_t)(t0 + ql) * ZW + Z_BG + hd * 128 + dh * 64;
;             bf16_t* yp = Y + (size_t)(t0 + ql) * 512 + hd * 128 + dh * 64;
; #pragma unroll
;             for (int d = 0; d < 2; ++d)
; #pragma unroll
;                 for (int g = 0; g < 4; ++g) {
;                     const int dl = d * 32 + 8 * g + 4 * h;
;                     const u32x2 gg = *(const u32x2*)(gp + dl);
;                     float gv[4] = {bflo(gg[0]), bfhi(gg[0]), bflo(gg[1]), bfhi(gg[1])};
;                     float ov[4];
; #pragma unroll
;                     for (int j = 0; j < 4; ++j) { const float sg = gv[j] * sigmoidf_(gv[j]); ov[j] = sg * o[d][4 * g + j] * rs; }
;                     u32x2 pk; pk[0] = cvt_pk_bf16(ov[0], ov[1]); pk[1] = cvt_pk_bf16(ov[2], ov[3]);
;                     *(u32x2*)(yp + dl) = pk;
;                 }
;         }
; #pragma unroll
;         for (int i = 0; i < 16; ++i) sacc[i] *= gam128;
;         {
;             const bf16_t* va = vtb + (size_t)(dvt * 32 + r) * L + p0 + 8 * h;
;             const bf16_t* kb = ktb + (size_t)(dt * 32 + r) * L + p0 + 8 * h;
; #pragma unroll 2
;             for (int ks = 0; ks < 8; ++ks) {
;                 const bf16x8 vf = *(const bf16x8*)(va + 16 * ks);
;                 const u32x4 kr = *(const u32x4*)(kb + 16 * ks);
;                 u32x4 kd;
; #pragma unroll
;                 for (int jj = 0; jj < 4; ++jj) {
;                     const int j0 = 16 * ks + 8 * h + 2 * jj;
;                     kd[jj] = cvt_pk_bf16(bflo(kr[jj]) * fexp2(lg2 * (float)(127 - j0)), bfhi(kr[jj]) * fexp2(lg2 * (float)(126 - j0)));
;                 }
;                 sacc = MFMA32(vf, __builtin_bit_cast(bf16x8, kd), sacc);
;             }
	s_nop 0
	v_pk_mul_f32 v[28:29], v[18:19], v[28:29] op_sel_hi:[0,1]
	v_cvt_pk_bf16_f32 v31, v28, v29
	v_mov_b64_e32 v[28:29], v[194:195]
	s_nop 0
	global_store_dwordx2 v[22:23], v[30:31], off offset:48
	v_lshlrev_b32_e32 v30, 16, v28
	v_mul_f32_e32 v19, 0xbfb8aa3b, v30
	v_exp_f32_e32 v19, v19
	v_and_b32_e32 v31, 0xffff0000, v28
	v_lshlrev_b32_e32 v28, 16, v29
	v_and_b32_e32 v29, 0xffff0000, v29
	v_add_f32_e32 v19, 1.0, v19
	v_rcp_f32_e32 v42, v19
	v_mul_f32_e32 v19, 0xbfb8aa3b, v31
	v_exp_f32_e32 v19, v19
	s_nop 0
	v_add_f32_e32 v19, 1.0, v19
	v_rcp_f32_e32 v43, v19
	s_nop 0
	v_pk_mul_f32 v[30:31], v[42:43], v[30:31]
	s_nop 0
	v_pk_mul_f32 v[30:31], v[40:41], v[30:31]
	s_nop 0
	v_pk_mul_f32 v[30:31], v[18:19], v[30:31] op_sel_hi:[0,1]
	v_mul_f32_e32 v19, 0xbfb8aa3b, v28
	v_exp_f32_e32 v19, v19
	v_cvt_pk_bf16_f32 v30, v30, v31
	v_add_f32_e32 v19, 1.0, v19
	v_rcp_f32_e32 v40, v19
	v_mul_f32_e32 v19, 0xbfb8aa3b, v29
	v_exp_f32_e32 v19, v19
	s_nop 0
	v_add_f32_e32 v19, 1.0, v19
	v_rcp_f32_e32 v41, v19
	s_nop 0
	v_pk_mul_f32 v[28:29], v[40:41], v[28:29]
	s_nop 0
	v_pk_mul_f32 v[28:29], v[38:39], v[28:29]
	s_nop 0
	v_pk_mul_f32 v[28:29], v[18:19], v[28:29] op_sel_hi:[0,1]
	v_cvt_pk_bf16_f32 v31, v28, v29
	v_mov_b64_e32 v[28:29], v[196:197]
	s_nop 0
	global_store_dwordx2 v[22:23], v[30:31], off offset:64
	v_lshlrev_b32_e32 v30, 16, v28
	v_mul_f32_e32 v19, 0xbfb8aa3b, v30
	v_exp_f32_e32 v19, v19
	v_and_b32_e32 v31, 0xffff0000, v28
	v_lshlrev_b32_e32 v28, 16, v29
	v_and_b32_e32 v29, 0xffff0000, v29
	v_add_f32_e32 v19, 1.0, v19
	v_rcp_f32_e32 v38, v19
	v_mul_f32_e32 v19, 0xbfb8aa3b, v31
	v_exp_f32_e32 v19, v19
	s_nop 0
	v_add_f32_e32 v19, 1.0, v19
	v_rcp_f32_e32 v39, v19
	s_nop 0
	v_pk_mul_f32 v[30:31], v[38:39], v[30:31]
	s_nop 0
	v_pk_mul_f32 v[30:31], v[36:37], v[30:31]
	s_nop 0
	v_pk_mul_f32 v[30:31], v[18:19], v[30:31] op_sel_hi:[0,1]
	v_mul_f32_e32 v19, 0xbfb8aa3b, v28
	v_exp_f32_e32 v19, v19
	v_cvt_pk_bf16_f32 v30, v30, v31
	v_add_f32_e32 v19, 1.0, v19
	v_rcp_f32_e32 v36, v19
	v_mul_f32_e32 v19, 0xbfb8aa3b, v29
	v_exp_f32_e32 v19, v19
	s_nop 0
	v_add_f32_e32 v19, 1.0, v19
	v_rcp_f32_e32 v37, v19
	s_nop 0
	v_pk_mul_f32 v[28:29], v[36:37], v[28:29]
	s_nop 0
	v_pk_mul_f32 v[28:29], v[34:35], v[28:29]
	s_nop 0
	v_pk_mul_f32 v[28:29], v[18:19], v[28:29] op_sel_hi:[0,1]
	v_cvt_pk_bf16_f32 v31, v28, v29
	v_mov_b64_e32 v[28:29], v[198:199]
	s_nop 0
	v_mov_b64_e32 v[24:25], v[200:201]
	s_nop 0
	global_store_dwordx2 v[22:23], v[30:31], off offset:80
	v_lshlrev_b32_e32 v30, 16, v28
	v_mul_f32_e32 v19, 0xbfb8aa3b, v30
	v_exp_f32_e32 v19, v19
	v_and_b32_e32 v31, 0xffff0000, v28
	v_lshlrev_b32_e32 v28, 16, v29
	v_and_b32_e32 v29, 0xffff0000, v29
	v_add_f32_e32 v19, 1.0, v19
	v_rcp_f32_e32 v34, v19
	v_mul_f32_e32 v19, 0xbfb8aa3b, v31
	v_exp_f32_e32 v19, v19
	s_nop 0
	v_add_f32_e32 v19, 1.0, v19
	v_rcp_f32_e32 v35, v19
	s_nop 0
	v_pk_mul_f32 v[30:31], v[34:35], v[30:31]
	s_nop 0
	v_pk_mul_f32 v[30:31], v[32:33], v[30:31]
	s_nop 0
	v_pk_mul_f32 v[30:31], v[18:19], v[30:31] op_sel_hi:[0,1]
	v_mul_f32_e32 v19, 0xbfb8aa3b, v28
	v_exp_f32_e32 v19, v19
	s_nop 0
	v_add_f32_e32 v19, 1.0, v19
	v_rcp_f32_e32 v32, v19
	v_mul_f32_e32 v19, 0xbfb8aa3b, v29
	v_exp_f32_e32 v19, v19
	s_nop 0
	v_add_f32_e32 v19, 1.0, v19
	v_rcp_f32_e32 v33, v19
	s_nop 0
	v_pk_mul_f32 v[28:29], v[32:33], v[28:29]
	s_nop 0
	v_pk_mul_f32 v[26:27], v[26:27], v[28:29]
	v_cvt_pk_bf16_f32 v28, v30, v31
	v_pk_mul_f32 v[26:27], v[18:19], v[26:27] op_sel_hi:[0,1]
	v_cvt_pk_bf16_f32 v29, v26, v27
	v_lshlrev_b32_e32 v26, 16, v24
	v_mul_f32_e32 v19, 0xbfb8aa3b, v26
	v_exp_f32_e32 v19, v19
	v_and_b32_e32 v27, 0xffff0000, v24
	global_store_dwordx2 v[22:23], v[28:29], off offset:96
	v_lshlrev_b32_e32 v24, 16, v25
	v_add_f32_e32 v19, 1.0, v19
	v_rcp_f32_e32 v28, v19
	v_mul_f32_e32 v19, 0xbfb8aa3b, v27
	v_exp_f32_e32 v19, v19
	v_and_b32_e32 v25, 0xffff0000, v25
	v_add_f32_e32 v19, 1.0, v19
	v_rcp_f32_e32 v29, v19
	s_nop 0
	v_pk_mul_f32 v[26:27], v[28:29], v[26:27]
	s_nop 0
	v_pk_mul_f32 v[20:21], v[20:21], v[26:27]
	s_nop 0
	v_pk_mul_f32 v[20:21], v[18:19], v[20:21] op_sel_hi:[0,1]
	v_mul_f32_e32 v19, 0xbfb8aa3b, v24
	v_exp_f32_e32 v19, v19
	s_nop 0
	v_add_f32_e32 v19, 1.0, v19
	v_rcp_f32_e32 v26, v19
	v_mul_f32_e32 v19, 0xbfb8aa3b, v25
	v_exp_f32_e32 v19, v19
	s_nop 0
	v_add_f32_e32 v19, 1.0, v19
	v_rcp_f32_e32 v27, v19
	s_nop 0
	v_pk_mul_f32 v[24:25], v[26:27], v[24:25]
	s_nop 0
	v_pk_mul_f32 v[16:17], v[16:17], v[24:25]
	v_mov_b64_e32 v[24:25], v[114:115]
	v_pk_mul_f32 v[16:17], v[18:19], v[16:17] op_sel_hi:[0,1]
	v_cvt_pk_bf16_f32 v18, v20, v21
	v_cvt_pk_bf16_f32 v19, v16, v17
	v_mov_b64_e32 v[26:27], v[112:113]
	global_store_dwordx2 v[22:23], v[18:19], off offset:112
	s_waitcnt vmcnt(22)
	v_add_u32_e32 v32, 127, v126
	v_add_u32_e32 v33, 126, v126
	v_cvt_f32_u32_e32 v32, v32
	v_cvt_f32_u32_e32 v33, v33
	v_lshlrev_b32_e32 v34, 16, v136
	v_and_b32_e32 v35, 0xffff0000, v136
	v_mul_f32_e32 v32, v93, v32
	v_mul_f32_e32 v33, v93, v33
	v_exp_f32_e32 v32, v32
	v_exp_f32_e32 v33, v33
	s_nop 0
	v_pk_mul_f32 v[32:33], v[32:33], v[34:35]
	s_nop 0
	v_cvt_pk_bf16_f32 v136, v32, v33
	v_add_u32_e32 v32, 125, v126
	v_add_u32_e32 v33, 124, v126
	v_cvt_f32_u32_e32 v32, v32
	v_cvt_f32_u32_e32 v33, v33
	v_lshlrev_b32_e32 v34, 16, v137
	v_and_b32_e32 v35, 0xffff0000, v137
	v_mul_f32_e32 v32, v93, v32
	v_mul_f32_e32 v33, v93, v33
	v_exp_f32_e32 v32, v32
	v_exp_f32_e32 v33, v33
	s_nop 0
	v_pk_mul_f32 v[32:33], v[32:33], v[34:35]
	s_nop 0
	v_cvt_pk_bf16_f32 v137, v32, v33
	v_add_u32_e32 v32, 123, v126
	v_add_u32_e32 v33, 122, v126
	v_cvt_f32_u32_e32 v32, v32
	v_cvt_f32_u32_e32 v33, v33
	v_lshlrev_b32_e32 v34, 16, v138
	v_and_b32_e32 v35, 0xffff0000, v138
	v_mul_f32_e32 v32, v93, v32
	v_mul_f32_e32 v33, v93, v33
	v_exp_f32_e32 v32, v32
	v_exp_f32_e32 v33, v33
	s_nop 0
	v_pk_mul_f32 v[32:33], v[32:33], v[34:35]
	s_nop 0
	v_cvt_pk_bf16_f32 v138, v32, v33
	v_add_u32_e32 v32, 121, v126
	v_add_u32_e32 v33, 120, v126
	v_cvt_f32_u32_e32 v32, v32
	v_cvt_f32_u32_e32 v33, v33
	v_lshlrev_b32_e32 v34, 16, v139
	v_and_b32_e32 v35, 0xffff0000, v139
	v_mul_f32_e32 v32, v93, v32
	v_mul_f32_e32 v33, v93, v33
	v_exp_f32_e32 v32, v32
	v_exp_f32_e32 v33, v33
	s_nop 0
	v_pk_mul_f32 v[32:33], v[32:33], v[34:35]
	s_nop 0
	v_cvt_pk_bf16_f32 v139, v32, v33
	s_nop 1
	v_mfma_f32_32x32x16_bf16 v[0:15], v[132:135], v[136:139], v[0:15]
	s_waitcnt vmcnt(20)
; #define MFMA32(a, b, c) __builtin_amdgcn_mfma_f32_32x32x16_bf16((a), (b), (c), 0, 0, 0)
; DEVINL unsigned cvt_pk_bf16(float lo, float hi) { const f32x2 v = {lo, hi}; return __builtin_bit_cast(unsigned, __builtin_convertvector(v, bf16x2v)); }
; DEVINL float bflo(unsigned u) { return __uint_as_float(u << 16); }
; DEVINL float bfhi(unsigned u) { return __uint_as_float(u & 0xffff0000u); }
; DEVINL float fexp2(float x) { return __builtin_amdgcn_exp2f(x); }
; DEVINL void ret_block(const Ctx& c, int b, int hd, unsigned char* lds) {
;     ...
;         {
;             const bf16_t* va = vtb + (size_t)(dvt * 32 + r) * L + p0 + 8 * h;
;             const bf16_t* kb = ktb + (size_t)(dt * 32 + r) * L + p0 + 8 * h;
; #pragma unroll 2
;             for (int ks = 0; ks < 8; ++ks) {
;                 const bf16x8 vf = *(const bf16x8*)(va + 16 * ks);
;                 const u32x4 kr = *(const u32x4*)(kb + 16 * ks);
;                 u32x4 kd;
; #pragma unroll
;                 for (int jj = 0; jj < 4; ++jj) {
;                     const int j0 = 16 * ks + 8 * h + 2 * jj;
;                     kd[jj] = cvt_pk_bf16(bflo(kr[jj]) * fexp2(lg2 * (float)(127 - j0)), bfhi(kr[jj]) * fexp2(lg2 * (float)(126 - j0)));
;                 }
;                 sacc = MFMA32(vf, __builtin_bit_cast(bf16x8, kd), sacc);
;             }
	v_add_u32_e32 v32, 111, v126
	v_add_u32_e32 v33, 110, v126
	v_cvt_f32_u32_e32 v32, v32
	v_cvt_f32_u32_e32 v33, v33
	v_lshlrev_b32_e32 v34, 16, v144
	v_and_b32_e32 v35, 0xffff0000, v144
	v_mul_f32_e32 v32, v93, v32
	v_mul_f32_e32 v33, v93, v33
	v_exp_f32_e32 v32, v32
	v_exp_f32_e32 v33, v33
	s_nop 0
	v_pk_mul_f32 v[32:33], v[32:33], v[34:35]
	s_nop 0
	v_cvt_pk_bf16_f32 v144, v32, v33
	v_add_u32_e32 v32, 109, v126
	v_add_u32_e32 v33, 108, v126
	v_cvt_f32_u32_e32 v32, v32
	v_cvt_f32_u32_e32 v33, v33
	v_lshlrev_b32_e32 v34, 16, v145
	v_and_b32_e32 v35, 0xffff0000, v145
	v_mul_f32_e32 v32, v93, v32
	v_mul_f32_e32 v33, v93, v33
	v_exp_f32_e32 v32, v32
	v_exp_f32_e32 v33, v33
	s_nop 0
	v_pk_mul_f32 v[32:33], v[32:33], v[34:35]
	s_nop 0
	v_cvt_pk_bf16_f32 v145, v32, v33
	v_add_u32_e32 v32, 107, v126
	v_add_u32_e32 v33, 106, v126
	v_cvt_f32_u32_e32 v32, v32
	v_cvt_f32_u32_e32 v33, v33
	v_lshlrev_b32_e32 v34, 16, v146
	v_and_b32_e32 v35, 0xffff0000, v146
	v_mul_f32_e32 v32, v93, v32
	v_mul_f32_e32 v33, v93, v33
	v_exp_f32_e32 v32, v32
	v_exp_f32_e32 v33, v33
	s_nop 0
	v_pk_mul_f32 v[32:33], v[32:33], v[34:35]
	s_nop 0
	v_cvt_pk_bf16_f32 v146, v32, v33
	v_add_u32_e32 v32, 105, v126
	v_add_u32_e32 v33, 104, v126
	v_cvt_f32_u32_e32 v32, v32
	v_cvt_f32_u32_e32 v33, v33
	v_lshlrev_b32_e32 v34, 16, v147
	v_and_b32_e32 v35, 0xffff0000, v147
	v_mul_f32_e32 v32, v93, v32
	v_mul_f32_e32 v33, v93, v33
	v_exp_f32_e32 v32, v32
	v_exp_f32_e32 v33, v33
	s_nop 0
	v_pk_mul_f32 v[32:33], v[32:33], v[34:35]
	s_nop 0
	v_cvt_pk_bf16_f32 v147, v32, v33
	s_nop 1
	v_mfma_f32_32x32x16_bf16 v[0:15], v[140:143], v[144:147], v[0:15]
	s_waitcnt vmcnt(18)
	v_add_u32_e32 v32, 95, v126
	v_add_u32_e32 v33, 94, v126
	v_cvt_f32_u32_e32 v32, v32
	v_cvt_f32_u32_e32 v33, v33
	v_lshlrev_b32_e32 v34, 16, v152
	v_and_b32_e32 v35, 0xffff0000, v152
	v_mul_f32_e32 v32, v93, v32
	v_mul_f32_e32 v33, v93, v33
	v_exp_f32_e32 v32, v32
	v_exp_f32_e32 v33, v33
	s_nop 0
	v_pk_mul_f32 v[32:33], v[32:33], v[34:35]
	s_nop 0
	v_cvt_pk_bf16_f32 v152, v32, v33
	v_add_u32_e32 v32, 93, v126
	v_add_u32_e32 v33, 92, v126
	v_cvt_f32_u32_e32 v32, v32
	v_cvt_f32_u32_e32 v33, v33
	v_lshlrev_b32_e32 v34, 16, v153
	v_and_b32_e32 v35, 0xffff0000, v153
	v_mul_f32_e32 v32, v93, v32
	v_mul_f32_e32 v33, v93, v33
	v_exp_f32_e32 v32, v32
	v_exp_f32_e32 v33, v33
	s_nop 0
	v_pk_mul_f32 v[32:33], v[32:33], v[34:35]
	s_nop 0
	v_cvt_pk_bf16_f32 v153, v32, v33
	v_add_u32_e32 v32, 91, v126
	v_add_u32_e32 v33, 90, v126
	v_cvt_f32_u32_e32 v32, v32
	v_cvt_f32_u32_e32 v33, v33
	v_lshlrev_b32_e32 v34, 16, v154
	v_and_b32_e32 v35, 0xffff0000, v154
	v_mul_f32_e32 v32, v93, v32
	v_mul_f32_e32 v33, v93, v33
	v_exp_f32_e32 v32, v32
	v_exp_f32_e32 v33, v33
	s_nop 0
	v_pk_mul_f32 v[32:33], v[32:33], v[34:35]
	s_nop 0
	v_cvt_pk_bf16_f32 v154, v32, v33
	v_add_u32_e32 v32, 89, v126
	v_add_u32_e32 v33, 88, v126
	v_cvt_f32_u32_e32 v32, v32
	v_cvt_f32_u32_e32 v33, v33
	v_lshlrev_b32_e32 v34, 16, v155
	v_and_b32_e32 v35, 0xffff0000, v155
	v_mul_f32_e32 v32, v93, v32
	v_mul_f32_e32 v33, v93, v33
	v_exp_f32_e32 v32, v32
	v_exp_f32_e32 v33, v33
	s_nop 0
	v_pk_mul_f32 v[32:33], v[32:33], v[34:35]
	s_nop 0
	v_cvt_pk_bf16_f32 v155, v32, v33
	s_nop 1
	v_mfma_f32_32x32x16_bf16 v[0:15], v[148:151], v[152:155], v[0:15]
	s_waitcnt vmcnt(16)
	v_add_u32_e32 v32, 79, v126
	v_add_u32_e32 v33, 78, v126
	v_cvt_f32_u32_e32 v32, v32
	v_cvt_f32_u32_e32 v33, v33
	v_lshlrev_b32_e32 v34, 16, v168
	v_and_b32_e32 v35, 0xffff0000, v168
	v_mul_f32_e32 v32, v93, v32
	v_mul_f32_e32 v33, v93, v33
	v_exp_f32_e32 v32, v32
	v_exp_f32_e32 v33, v33
	s_nop 0
	v_pk_mul_f32 v[32:33], v[32:33], v[34:35]
	s_nop 0
	v_cvt_pk_bf16_f32 v168, v32, v33
	v_add_u32_e32 v32, 77, v126
	v_add_u32_e32 v33, 76, v126
	v_cvt_f32_u32_e32 v32, v32
	v_cvt_f32_u32_e32 v33, v33
	v_lshlrev_b32_e32 v34, 16, v169
	v_and_b32_e32 v35, 0xffff0000, v169
	v_mul_f32_e32 v32, v93, v32
	v_mul_f32_e32 v33, v93, v33
	v_exp_f32_e32 v32, v32
	v_exp_f32_e32 v33, v33
	s_nop 0
	v_pk_mul_f32 v[32:33], v[32:33], v[34:35]
	s_nop 0
	v_cvt_pk_bf16_f32 v169, v32, v33
	v_add_u32_e32 v32, 75, v126
	v_add_u32_e32 v33, 74, v126
	v_cvt_f32_u32_e32 v32, v32
	v_cvt_f32_u32_e32 v33, v33
	v_lshlrev_b32_e32 v34, 16, v170
	v_and_b32_e32 v35, 0xffff0000, v170
	v_mul_f32_e32 v32, v93, v32
	v_mul_f32_e32 v33, v93, v33
	v_exp_f32_e32 v32, v32
	v_exp_f32_e32 v33, v33
	s_nop 0
	v_pk_mul_f32 v[32:33], v[32:33], v[34:35]
	s_nop 0
	v_cvt_pk_bf16_f32 v170, v32, v33
	v_add_u32_e32 v32, 73, v126
	v_add_u32_e32 v33, 72, v126
	v_cvt_f32_u32_e32 v32, v32
	v_cvt_f32_u32_e32 v33, v33
	v_lshlrev_b32_e32 v34, 16, v171
	v_and_b32_e32 v35, 0xffff0000, v171
	v_mul_f32_e32 v32, v93, v32
	v_mul_f32_e32 v33, v93, v33
	v_exp_f32_e32 v32, v32
	v_exp_f32_e32 v33, v33
	s_nop 0
	v_pk_mul_f32 v[32:33], v[32:33], v[34:35]
	s_nop 0
	v_cvt_pk_bf16_f32 v171, v32, v33
	s_nop 1
	v_mfma_f32_32x32x16_bf16 v[0:15], v[156:159], v[168:171], v[0:15]
	s_waitcnt vmcnt(14)
; #define MFMA32(a, b, c) __builtin_amdgcn_mfma_f32_32x32x16_bf16((a), (b), (c), 0, 0, 0)
; DEVINL unsigned cvt_pk_bf16(float lo, float hi) { const f32x2 v = {lo, hi}; return __builtin_bit_cast(unsigned, __builtin_convertvector(v, bf16x2v)); }
; DEVINL float bflo(unsigned u) { return __uint_as_float(u << 16); }
; DEVINL float bfhi(unsigned u) { return __uint_as_float(u & 0xffff0000u); }
; DEVINL float fexp2(float x) { return __builtin_amdgcn_exp2f(x); }
; DEVINL void ret_block(const Ctx& c, int b, int hd, unsigned char* lds) {
;     ...
;     for (int ch = 0; ch < L / 128; ++ch) {
;         const int t0 = b * L + ch * 128, p0 = ch * 128;
;     ...
; #pragma unroll
;         for (int i = 0; i < 16; ++i) sacc[i] *= gam128;
;         {
;             const bf16_t* va = vtb + (size_t)(dvt * 32 + r) * L + p0 + 8 * h;
;             const bf16_t* kb = ktb + (size_t)(dt * 32 + r) * L + p0 + 8 * h;
; #pragma unroll 2
;             for (int ks = 0; ks < 8; ++ks) {
;                 const bf16x8 vf = *(const bf16x8*)(va + 16 * ks);
;                 const u32x4 kr = *(const u32x4*)(kb + 16 * ks);
;                 u32x4 kd;
; #pragma unroll
;                 for (int jj = 0; jj < 4; ++jj) {
;                     const int j0 = 16 * ks + 8 * h + 2 * jj;
;                     kd[jj] = cvt_pk_bf16(bflo(kr[jj]) * fexp2(lg2 * (float)(127 - j0)), bfhi(kr[jj]) * fexp2(lg2 * (float)(126 - j0)));
;                 }
;                 sacc = MFMA32(vf, __builtin_bit_cast(bf16x8, kd), sacc);
;             }
;         }
	v_add_u32_e32 v32, 63, v126
	v_add_u32_e32 v33, 62, v126
	v_cvt_f32_u32_e32 v32, v32
	v_cvt_f32_u32_e32 v33, v33
	v_lshlrev_b32_e32 v34, 16, v176
	v_and_b32_e32 v35, 0xffff0000, v176
	v_mul_f32_e32 v32, v93, v32
	v_mul_f32_e32 v33, v93, v33
	v_exp_f32_e32 v32, v32
	v_exp_f32_e32 v33, v33
	s_nop 0
	v_pk_mul_f32 v[32:33], v[32:33], v[34:35]
	s_nop 0
	v_cvt_pk_bf16_f32 v176, v32, v33
	v_add_u32_e32 v32, 61, v126
	v_add_u32_e32 v33, 60, v126
	v_cvt_f32_u32_e32 v32, v32
	v_cvt_f32_u32_e32 v33, v33
	v_lshlrev_b32_e32 v34, 16, v177
	v_and_b32_e32 v35, 0xffff0000, v177
	v_mul_f32_e32 v32, v93, v32
	v_mul_f32_e32 v33, v93, v33
	v_exp_f32_e32 v32, v32
	v_exp_f32_e32 v33, v33
	s_nop 0
	v_pk_mul_f32 v[32:33], v[32:33], v[34:35]
	s_nop 0
	v_cvt_pk_bf16_f32 v177, v32, v33
	v_add_u32_e32 v32, 59, v126
	v_add_u32_e32 v33, 58, v126
	v_cvt_f32_u32_e32 v32, v32
	v_cvt_f32_u32_e32 v33, v33
	v_lshlrev_b32_e32 v34, 16, v178
	v_and_b32_e32 v35, 0xffff0000, v178
	v_mul_f32_e32 v32, v93, v32
	v_mul_f32_e32 v33, v93, v33
	v_exp_f32_e32 v32, v32
	v_exp_f32_e32 v33, v33
	s_nop 0
	v_pk_mul_f32 v[32:33], v[32:33], v[34:35]
	s_nop 0
	v_cvt_pk_bf16_f32 v178, v32, v33
	v_add_u32_e32 v32, 57, v126
	v_add_u32_e32 v33, 56, v126
	v_cvt_f32_u32_e32 v32, v32
	v_cvt_f32_u32_e32 v33, v33
	v_lshlrev_b32_e32 v34, 16, v179
	v_and_b32_e32 v35, 0xffff0000, v179
	v_mul_f32_e32 v32, v93, v32
	v_mul_f32_e32 v33, v93, v33
	v_exp_f32_e32 v32, v32
	v_exp_f32_e32 v33, v33
	s_nop 0
	v_pk_mul_f32 v[32:33], v[32:33], v[34:35]
	s_nop 0
	v_cvt_pk_bf16_f32 v179, v32, v33
	s_nop 1
	v_mfma_f32_32x32x16_bf16 v[0:15], v[172:175], v[176:179], v[0:15]
	s_waitcnt vmcnt(12)
	v_add_u32_e32 v32, 47, v126
	v_add_u32_e32 v33, 46, v126
	v_cvt_f32_u32_e32 v32, v32
	v_cvt_f32_u32_e32 v33, v33
	v_lshlrev_b32_e32 v34, 16, v208
	v_and_b32_e32 v35, 0xffff0000, v208
	v_mul_f32_e32 v32, v93, v32
	v_mul_f32_e32 v33, v93, v33
	v_exp_f32_e32 v32, v32
	v_exp_f32_e32 v33, v33
	s_nop 0
	v_pk_mul_f32 v[32:33], v[32:33], v[34:35]
	s_nop 0
	v_cvt_pk_bf16_f32 v208, v32, v33
	v_add_u32_e32 v32, 45, v126
	v_add_u32_e32 v33, 44, v126
	v_cvt_f32_u32_e32 v32, v32
	v_cvt_f32_u32_e32 v33, v33
	v_lshlrev_b32_e32 v34, 16, v209
	v_and_b32_e32 v35, 0xffff0000, v209
	v_mul_f32_e32 v32, v93, v32
	v_mul_f32_e32 v33, v93, v33
	v_exp_f32_e32 v32, v32
	v_exp_f32_e32 v33, v33
	s_nop 0
	v_pk_mul_f32 v[32:33], v[32:33], v[34:35]
	s_nop 0
	v_cvt_pk_bf16_f32 v209, v32, v33
	v_add_u32_e32 v32, 43, v126
	v_add_u32_e32 v33, 42, v126
	v_cvt_f32_u32_e32 v32, v32
	v_cvt_f32_u32_e32 v33, v33
	v_lshlrev_b32_e32 v34, 16, v210
	v_and_b32_e32 v35, 0xffff0000, v210
	v_mul_f32_e32 v32, v93, v32
	v_mul_f32_e32 v33, v93, v33
	v_exp_f32_e32 v32, v32
	v_exp_f32_e32 v33, v33
	s_nop 0
	v_pk_mul_f32 v[32:33], v[32:33], v[34:35]
	s_nop 0
	v_cvt_pk_bf16_f32 v210, v32, v33
	v_add_u32_e32 v32, 41, v126
	v_add_u32_e32 v33, 40, v126
	v_cvt_f32_u32_e32 v32, v32
	v_cvt_f32_u32_e32 v33, v33
	v_lshlrev_b32_e32 v34, 16, v211
	v_and_b32_e32 v35, 0xffff0000, v211
	v_mul_f32_e32 v32, v93, v32
	v_mul_f32_e32 v33, v93, v33
	v_exp_f32_e32 v32, v32
	v_exp_f32_e32 v33, v33
	s_nop 0
	v_pk_mul_f32 v[32:33], v[32:33], v[34:35]
	s_nop 0
	v_cvt_pk_bf16_f32 v211, v32, v33
	s_nop 1
	v_mfma_f32_32x32x16_bf16 v[0:15], v[180:183], v[208:211], v[0:15]
	s_waitcnt vmcnt(10)
	v_add_u32_e32 v32, 31, v126
	v_add_u32_e32 v33, 30, v126
	v_cvt_f32_u32_e32 v32, v32
	v_cvt_f32_u32_e32 v33, v33
	v_lshlrev_b32_e32 v34, 16, v216
	v_and_b32_e32 v35, 0xffff0000, v216
	v_mul_f32_e32 v32, v93, v32
	v_mul_f32_e32 v33, v93, v33
	v_exp_f32_e32 v32, v32
	v_exp_f32_e32 v33, v33
	s_nop 0
	v_pk_mul_f32 v[32:33], v[32:33], v[34:35]
	s_nop 0
	v_cvt_pk_bf16_f32 v216, v32, v33
	v_add_u32_e32 v32, 29, v126
	v_add_u32_e32 v33, 28, v126
	v_cvt_f32_u32_e32 v32, v32
	v_cvt_f32_u32_e32 v33, v33
	v_lshlrev_b32_e32 v34, 16, v217
	v_and_b32_e32 v35, 0xffff0000, v217
	v_mul_f32_e32 v32, v93, v32
	v_mul_f32_e32 v33, v93, v33
	v_exp_f32_e32 v32, v32
	v_exp_f32_e32 v33, v33
	s_nop 0
	v_pk_mul_f32 v[32:33], v[32:33], v[34:35]
	s_nop 0
	v_cvt_pk_bf16_f32 v217, v32, v33
	v_add_u32_e32 v32, 27, v126
	v_add_u32_e32 v33, 26, v126
	v_cvt_f32_u32_e32 v32, v32
	v_cvt_f32_u32_e32 v33, v33
	v_lshlrev_b32_e32 v34, 16, v218
	v_and_b32_e32 v35, 0xffff0000, v218
	v_mul_f32_e32 v32, v93, v32
	v_mul_f32_e32 v33, v93, v33
	v_exp_f32_e32 v32, v32
	v_exp_f32_e32 v33, v33
	s_nop 0
	v_pk_mul_f32 v[32:33], v[32:33], v[34:35]
	s_nop 0
	v_cvt_pk_bf16_f32 v218, v32, v33
	v_add_u32_e32 v32, 25, v126
	v_add_u32_e32 v33, 24, v126
	v_cvt_f32_u32_e32 v32, v32
	v_cvt_f32_u32_e32 v33, v33
	v_lshlrev_b32_e32 v34, 16, v219
	v_and_b32_e32 v35, 0xffff0000, v219
	v_mul_f32_e32 v32, v93, v32
	v_mul_f32_e32 v33, v93, v33
	v_exp_f32_e32 v32, v32
	v_exp_f32_e32 v33, v33
	s_nop 0
	v_pk_mul_f32 v[32:33], v[32:33], v[34:35]
	s_nop 0
	v_cvt_pk_bf16_f32 v219, v32, v33
	s_nop 1
	v_mfma_f32_32x32x16_bf16 v[0:15], v[212:215], v[216:219], v[0:15]
	s_waitcnt vmcnt(8)
	v_add_u32_e32 v32, 15, v126
	v_add_u32_e32 v33, 14, v126
	v_cvt_f32_u32_e32 v32, v32
	v_cvt_f32_u32_e32 v33, v33
	v_lshlrev_b32_e32 v34, 16, v224
	v_and_b32_e32 v35, 0xffff0000, v224
	v_mul_f32_e32 v32, v93, v32
	v_mul_f32_e32 v33, v93, v33
	v_exp_f32_e32 v32, v32
	v_exp_f32_e32 v33, v33
	s_nop 0
	v_pk_mul_f32 v[32:33], v[32:33], v[34:35]
	s_nop 0
	v_cvt_pk_bf16_f32 v224, v32, v33
	v_add_u32_e32 v32, 13, v126
	v_add_u32_e32 v33, 12, v126
	v_cvt_f32_u32_e32 v32, v32
	v_cvt_f32_u32_e32 v33, v33
	v_lshlrev_b32_e32 v34, 16, v225
	v_and_b32_e32 v35, 0xffff0000, v225
	v_mul_f32_e32 v32, v93, v32
	v_mul_f32_e32 v33, v93, v33
	v_exp_f32_e32 v32, v32
	v_exp_f32_e32 v33, v33
	s_nop 0
	v_pk_mul_f32 v[32:33], v[32:33], v[34:35]
	s_nop 0
	v_cvt_pk_bf16_f32 v225, v32, v33
	v_add_u32_e32 v32, 11, v126
	v_add_u32_e32 v33, 10, v126
	v_cvt_f32_u32_e32 v32, v32
	v_cvt_f32_u32_e32 v33, v33
	v_lshlrev_b32_e32 v34, 16, v226
	v_and_b32_e32 v35, 0xffff0000, v226
	v_mul_f32_e32 v32, v93, v32
	v_mul_f32_e32 v33, v93, v33
	v_exp_f32_e32 v32, v32
	v_exp_f32_e32 v33, v33
	s_nop 0
	v_pk_mul_f32 v[32:33], v[32:33], v[34:35]
	s_nop 0
	v_cvt_pk_bf16_f32 v226, v32, v33
	v_add_u32_e32 v32, 9, v126
	v_add_u32_e32 v33, 8, v126
	v_cvt_f32_u32_e32 v32, v32
	v_cvt_f32_u32_e32 v33, v33
	v_lshlrev_b32_e32 v34, 16, v227
	v_and_b32_e32 v35, 0xffff0000, v227
	v_mul_f32_e32 v32, v93, v32
	v_mul_f32_e32 v33, v93, v33
	v_exp_f32_e32 v32, v32
	v_exp_f32_e32 v33, v33
	s_nop 0
	v_pk_mul_f32 v[32:33], v[32:33], v[34:35]
	s_nop 0
	v_cvt_pk_bf16_f32 v227, v32, v33
	s_nop 1
	v_mfma_f32_32x32x16_bf16 v[0:15], v[220:223], v[224:227], v[0:15]
	s_add_i32 s7, s7, 1
	v_add_u32_e32 v125, 0x80, v125
	v_lshl_add_u64 v[108:109], v[108:109], 0, s[84:85]
	v_lshl_add_u64 v[110:111], v[110:111], 0, s[84:85]
	v_lshl_add_u64 v[112:113], v[112:113], 0, s[84:85]
	s_cmp_eq_u32 s7, s100
	v_lshl_add_u64 v[114:115], v[114:115], 0, s[84:85]
	s_cbranch_scc0 .LBB0_268

;     DEVINL bf16_t* RW() const { return (bf16_t*)(ws + OFF_RW); }
;     DEVINL bf16_t* Y() const { return (bf16_t*)(ws + OFF_Y); }
; #define TID (opq_v((int)threadIdx.x))
; DEVINL void rwkv_scan(const Ctx& c, int layer, int b, int hd, const unsigned* cnt3, int nP, float* lds) {
;     float* sy = lds + 3 * STG;
;     const int tid = TID, lane = tid & 63, w = tid >> 6;
;     const bf16_t* rwbase = c.RW();
;     const bf16_t* GG = c.RW() + (size_t)6 * T * 512;
;     bf16_t* Y = c.Y() + (size_t)2 * T * 512;
;     const int rp = lane >> 3, jo = lane & 7, i0 = 16 * (w & 3) + 2 * rp;
;     f32x2 S0[4], S1[4];
; #pragma unroll
;     for (int j = 0; j < 4; ++j) { S0[j] = (f32x2){0.f, 0.f}; S1[j] = (f32x2){0.f, 0.f}; }
;     const float lng = c.in[I_LNG][layer * 512 + hd * 64 + lane], lnb = c.in[I_LNB][layer * 512 + hd * 64 + lane], rkv = c.in[I_RK][layer * 512 + hd * 64 + lane];
;     __syncthreads();
;     unsigned have = (unsigned)(layer * 16 + 1);
;     rw_wait_ready(cnt3, have, nP);
;     rw_stage(rwbase, b * L, hd, lds, tid, NTHR);
;     u32x4 raw[4];
; #pragma unroll
;     for (int k = 0; k < 4; ++k) raw[k] = (u32x4){0u, 0u, 0u, 0u};
;     if (w >= 4) rw_stage_load(raw, rwbase, b * L + TC, hd, tid - 256);
;     __syncthreads();
.Lscan_prio_done:
	s_mul_i32 s0, s95, 3
	s_ashr_i32 s1, s0, 31
	s_lshl_b64 s[0:1], s[0:1], 2
	v_readlane_b32 s4, v247, 28
	s_add_u32 s30, s4, s0
	v_readlane_b32 s0, v247, 29
	s_addc_u32 s31, s0, s1
	v_readlane_b32 s0, v245, 32
	s_cmp_lt_i32 s95, 32
	v_readlane_b32 s1, v245, 33
	s_mov_b32 s34, 2
	s_mov_b32 s20, s0
	s_lshl_b32 s1, s0, 9
	s_lshl_b32 s0, s95, 6
	v_mov_b32_e32 v146, v160
	s_and_b32 s0, s0, 0x1c0
	s_or_b32 s1, s0, s1
	v_and_b32_e32 v20, 63, v146
	s_waitcnt vmcnt(0)
	v_or_b32_e32 v0, s1, v20
	v_ashrrev_i32_e32 v1, 31, v0
	v_readlane_b32 s4, v246, 59
	v_lshlrev_b64 v[0:1], 2, v[0:1]
	v_readlane_b32 s14, v245, 5
	v_readlane_b32 s15, v245, 6
	v_readlane_b32 s12, v245, 3
	v_readlane_b32 s13, v245, 4
	v_readlane_b32 s16, v245, 7
	v_readlane_b32 s17, v245, 8
	v_lshl_add_u64 v[2:3], s[14:15], 0, v[0:1]
	global_load_dword v147, v[2:3], off
	v_lshl_add_u64 v[2:3], s[16:17], 0, v[0:1]
	v_lshl_add_u64 v[0:1], s[12:13], 0, v[0:1]
	global_load_dword v148, v[2:3], off
	global_load_dword v149, v[0:1], off
	v_readlane_b32 s10, v245, 1
	v_readlane_b32 s11, v245, 2
	s_lshl_b32 s10, s20, 4
	s_mov_b32 s66, 0
	s_mov_b32 s11, 0x1100000
	v_readlane_b32 s5, v246, 60
	v_readlane_b32 s6, v246, 61
	v_readlane_b32 s7, v246, 62
	v_readlane_b32 s8, v246, 63
	v_readlane_b32 s9, v245, 0
	v_readlane_b32 s18, v245, 9
	v_readlane_b32 s19, v245, 10
	s_waitcnt vmcnt(0)
	s_barrier
	s_branch .LBB0_296

; DEVINL void rwkv_scan(const Ctx& c, int layer, int b, int hd, const unsigned* cnt3, int nP, float* lds) {
;     ...
;     if (w >= 4) rw_stage_load(raw, rwbase, b * L + TC, hd, tid - 256);
;     __syncthreads();
;     for (int ch = 0; ch <= NCH; ++ch) {
;         if (w < 4) {
;             if (ch < NCH) {
;                 const float* buf = lds + (ch % 3) * STG;
;                 float* syw = sy + (ch & 1) * TC * 64;
;                 RwOps ops[3];
;                 rw_load_ops(ops[0], buf, 0, jo, i0);
;                 rw_load_ops(ops[1], buf, 1, jo, i0);
; #pragma unroll
;                 for (int tt = 0; tt < TC; ++tt) {
;                     if (tt + 2 < TC) rw_load_ops(ops[(tt + 2) % 3], buf, tt + 2, jo, i0);
;                     const f32x2 y = rw_step(S0, S1, ops[tt % 3]);
;                     *(f32x2*)(syw + tt * 64 + i0) = y;
;                 }
;             }
;         } else {
;             const int ht = tid - 256, hw = w - 4;
;             if (ch + 1 < NCH) rw_stage_write(raw, lds + ((ch + 1) % 3) * STG, ht);
;             if (ch + 2 < NCH) {
;                 const unsigned need = (unsigned)(layer * 16 + (ch + 2) / (7 * nP) + 1);
;                 if (need > have) { rw_wait_ready(cnt3, need, nP); have = need; }
;                 rw_stage_load(raw, rwbase, b * L + (ch + 2) * TC, hd, ht);
.LBB0_315:
	s_or_b64 exec, exec, s[4:5]
	v_lshrrev_b32_e32 v23, 2, v146
	s_movk_i32 s6, 0x280
	v_lshlrev_b32_e32 v24, 4, v150
	v_and_b32_e32 v23, 14, v23
	v_cmp_gt_u32_e64 s[8:9], s6, v21
	s_movk_i32 s6, 0x180
	v_and_or_b32 v153, v24, 48, v23
	s_or_b32 s36, s10, 1
	v_readlane_b32 s4, v246, 31
	v_lshlrev_b32_e32 v23, 5, v21
	v_cmp_gt_u32_e64 s[10:11], s6, v21
	v_readlane_b32 s6, v245, 28
	v_lshl_add_u32 v154, v153, 2, s4
	v_and_b32_e32 v24, 0xf00, v23
	v_and_b32_e32 v23, 0xe0, v23
	s_movk_i32 s4, 0x380
	v_lshlrev_b64 v[18:19], 1, v[18:19]
	v_readlane_b32 s7, v245, 29
	v_add3_u32 v156, 0, v24, v23
	v_cmp_gt_u32_e64 s[4:5], s4, v21
	v_cmp_ne_u32_e64 s[22:23], 1, v22
	v_lshlrev_b32_e32 v157, 12, v22
	v_cmp_gt_u32_e64 s[12:13], s39, v21
	v_ashrrev_i32_e32 v21, 7, v21
	v_lshl_add_u64 v[22:23], s[6:7], 0, v[18:19]
	v_lshl_add_u64 v[134:135], v[16:17], 1, v[22:23]
	s_mov_b32 s6, 0x1100000
	v_add_u32_e32 v16, 2, v21
	v_mad_i64_i32 v[138:139], s[18:19], v16, s6, 0
	v_add_u32_e32 v16, 4, v21
	v_mad_i64_i32 v[140:141], s[20:21], v16, s6, 0
	v_add_u32_e32 v16, 6, v21
	v_mad_i64_i32 v[142:143], s[24:25], v16, s6, 0
	v_readlane_b32 s24, v247, 24
	v_readlane_b32 s25, v247, 25
	s_mul_i32 s37, s34, 8
	v_lshlrev_b32_e32 v64, 1, v20
	v_lshl_add_u64 v[16:17], s[24:25], 0, v[18:19]
	v_lshl_add_u64 v[144:145], v[16:17], 0, v[64:65]
	v_cvt_f32_ubyte0_e32 v17, s37
	v_rcp_iflag_f32_e32 v17, v17
	s_sub_i32 s24, 0, s37
	v_add_u32_e32 v155, -4, v150
	v_add_u32_e32 v158, 4, v150
	v_mul_f32_e32 v17, 0x4f7ffffe, v17
	v_cvt_u32_f32_e32 v17, v17
	v_add_u32_e32 v159, 8, v150
	v_mad_i64_i32 v[136:137], s[16:17], v21, s6, 0
	v_readfirstlane_b32 s25, v17
	s_mul_i32 s24, s24, s25
	v_lshl_or_b32 v16, v155, 6, v20
	v_lshl_or_b32 v18, v158, 6, v20
	v_lshl_or_b32 v19, v159, 6, v20
	s_mul_hi_u32 s24, s25, s24
	v_mov_b32_e32 v64, v65
	v_cmp_lt_i32_e64 s[0:1], 3, v150
	v_cmp_gt_i32_e64 s[14:15], 7, v21
	v_cmp_gt_i32_e64 s[16:17], 5, v21
	v_cmp_gt_i32_e64 s[18:19], 3, v21
	v_cmp_gt_i32_e64 s[20:21], 1, v21
	s_mov_b32 s38, 0
	s_add_i32 s39, s25, s24
	v_mov_b32_e32 v171, s36
	v_lshlrev_b32_e32 v168, 2, v16
	v_lshlrev_b32_e32 v169, 2, v18
	v_lshlrev_b32_e32 v170, 2, v19
	v_mov_b64_e32 v[24:25], v[64:65]
	v_mov_b64_e32 v[26:27], v[64:65]
	v_mov_b64_e32 v[40:41], v[64:65]
	v_mov_b64_e32 v[42:43], v[64:65]
	v_mov_b64_e32 v[44:45], v[64:65]
	v_mov_b64_e32 v[46:47], v[64:65]
	v_mov_b64_e32 v[60:61], v[64:65]
	v_mov_b64_e32 v[28:29], v[64:65]
	s_mov_b64 s[28:29], exec
	s_and_b64 exec, exec, s[0:1]
	s_cbranch_execz .Lsl_pro_done
	v_add_u32_e32 v16, 32, v151
	v_ashrrev_i32_e32 v17, 31, v16
	v_lshlrev_b64 v[16:17], 10, v[16:17]
	v_lshl_add_u64 v[16:17], v[134:135], 0, v[16:17]

; __global__ void __launch_bounds__(NTHR) fwd_megakernel(Params P) {
;     extern __shared__ __attribute__((aligned(16))) unsigned char lds[];
	.amdhsa_kernel _Z14fwd_megakernel6Params
		.amdhsa_group_segment_fixed_size 16384
		.amdhsa_private_segment_fixed_size 0
		.amdhsa_kernarg_size 512
		.amdhsa_user_sgpr_count 2
		.amdhsa_user_sgpr_dispatch_ptr 0
		.amdhsa_user_sgpr_queue_ptr 0
		.amdhsa_user_sgpr_kernarg_segment_ptr 1
		.amdhsa_user_sgpr_dispatch_id 0
		.amdhsa_user_sgpr_kernarg_preload_length 0
		.amdhsa_user_sgpr_kernarg_preload_offset 0
		.amdhsa_user_sgpr_private_segment_size 0
		.amdhsa_uses_dynamic_stack 0
		.amdhsa_enable_private_segment 0
		.amdhsa_system_sgpr_workgroup_id_x 1
		.amdhsa_system_sgpr_workgroup_id_y 0
		.amdhsa_system_sgpr_workgroup_id_z 0
		.amdhsa_system_sgpr_workgroup_info 0
		.amdhsa_system_vgpr_workitem_id 2
		.amdhsa_next_free_vgpr 256
		.amdhsa_next_free_sgpr 102
		.amdhsa_accum_offset 256
		.amdhsa_reserve_vcc 1
		.amdhsa_float_round_mode_32 0
		.amdhsa_float_round_mode_16_64 0
		.amdhsa_float_denorm_mode_32 3
		.amdhsa_float_denorm_mode_16_64 3
		.amdhsa_dx10_clamp 1
		.amdhsa_ieee_mode 1
		.amdhsa_fp16_overflow 0
		.amdhsa_tg_split 0
		.amdhsa_exception_fp_ieee_invalid_op 0
		.amdhsa_exception_fp_denorm_src 0
		.amdhsa_exception_fp_ieee_div_zero 0
		.amdhsa_exception_fp_ieee_overflow 0
		.amdhsa_exception_fp_ieee_underflow 0
		.amdhsa_exception_fp_ieee_inexact 0
		.amdhsa_exception_int_div_zero 0
	.end_amdhsa_kernel

; __global__ void __launch_bounds__(NTHR) fwd_megakernel(Params P) {
;     extern __shared__ __attribute__((aligned(16))) unsigned char lds[];
amdhsa.kernels:
  - .agpr_count:     0
    .args:
      - .offset:         0
        .size:           256
        .value_kind:     by_value
      - .offset:         256
        .size:           4
        .value_kind:     hidden_block_count_x
      - .offset:         260
        .size:           4
        .value_kind:     hidden_block_count_y
      - .offset:         264
        .size:           4
        .value_kind:     hidden_block_count_z
      - .offset:         268
        .size:           2
        .value_kind:     hidden_group_size_x
      - .offset:         270
        .size:           2
        .value_kind:     hidden_group_size_y
      - .offset:         272
        .size:           2
        .value_kind:     hidden_group_size_z
      - .offset:         274
        .size:           2
        .value_kind:     hidden_remainder_x
      - .offset:         276
        .size:           2
        .value_kind:     hidden_remainder_y
      - .offset:         278
        .size:           2
        .value_kind:     hidden_remainder_z
      - .offset:         296
        .size:           8
        .value_kind:     hidden_global_offset_x
      - .offset:         304
        .size:           8
        .value_kind:     hidden_global_offset_y
      - .offset:         312
        .size:           8
        .value_kind:     hidden_global_offset_z
      - .offset:         320
        .size:           2
        .value_kind:     hidden_grid_dims
      - .offset:         344
        .size:           8
        .value_kind:     hidden_multigrid_sync_arg
      - .offset:         376
        .size:           4
        .value_kind:     hidden_dynamic_lds_size
    .group_segment_fixed_size: 16384
    .kernarg_segment_align: 8
    .kernarg_segment_size: 512
    .language:       OpenCL C
    .language_version:
      - 2
      - 0
    .max_flat_workgroup_size: 512
    .name:           _Z14fwd_megakernel6Params
    .private_segment_fixed_size: 0
    .sgpr_count:     108
    .sgpr_spill_count: 171
    .symbol:         _Z14fwd_megakernel6Params.kd
    .uniform_work_group_size: 1
    .uses_dynamic_stack: false
    .vgpr_count:     256
    .vgpr_spill_count: 0
    .wavefront_size: 64
